# GEMM epilogue head_ss: also drop the now-pointless s_waitcnt lgkmcnt(0) between the permlane-swap groups (only ds_write_b32 in flight; drained at the exchange barrier)
# speedup vs baseline: 1.0030x; 1.0030x over previous
; __device__ __forceinline__ void head_ss(const f32x4 (&v)[2][2][4][2], float (&tot)[2][4][2], LAS float* X, int wr, int wc, int fr, int fq) {
;     ...
;                 const f32x4 a = v[ai][bj][m][0], b = v[ai][bj][m][1];
;                 float s = (a[0] * a[0] + a[1] * a[1]) + (a[2] * a[2] + a[3] * a[3]) + (b[0] * b[0] + b[1] * b[1]) + (b[2] * b[2] + b[3] * b[3]);
;                 s += __shfl_xor(s, 16); s += __shfl_xor(s, 32);
;                 if (fq == 0) X[((ai * 128 + wr * 64 + m * 16 + fr) * 2 + bj) * 4 + wc] = s;
.LBB0_233:
	s_and_b64 vcc, exec, s[0:1]
	s_cbranch_vccnz .LBB0_267
	v_mul_f32_e32 v94, v141, v141
	v_mul_f32_e32 v95, v143, v143
	v_fmac_f32_e32 v94, v140, v140
	v_fmac_f32_e32 v95, v142, v142
	v_and_b32_e32 v93, 64, v206
	v_add_f32_e32 v94, v94, v95
	v_mul_f32_e32 v95, v137, v137
	v_xor_b32_e32 v92, 16, v206
	v_add_u32_e32 v93, 64, v93
	v_fmac_f32_e32 v95, v136, v136
	v_cmp_lt_i32_e32 vcc, v92, v93
	v_add_f32_e32 v94, v94, v95
	v_mul_f32_e32 v95, v139, v139
	v_cndmask_b32_e32 v92, v206, v92, vcc
	v_fmac_f32_e32 v95, v138, v138
	v_lshlrev_b32_e32 v92, 2, v92
	v_add_f32_e32 v95, v95, v94
	v_mov_b32_e32 v100, v95
	s_nop 1
	v_permlane16_swap_b32_e32 v100, v95
	v_xor_b32_e32 v94, 32, v206
	v_cmp_lt_i32_e32 vcc, v94, v93
	v_readlane_b32 s7, v242, 47
	v_add_f32_e32 v95, v95, v100
	v_cndmask_b32_e32 v93, v206, v94, vcc
	v_lshlrev_b32_e32 v94, 2, v93
	v_mov_b32_e32 v100, v95
	s_nop 1
	v_permlane32_swap_b32_e32 v100, v95
	v_add_u32_e32 v93, s7, v200
	s_and_saveexec_b64 s[20:21], s[8:9]
	s_cbranch_execz .LBB0_236
	v_add_f32_e32 v95, v95, v100
	ds_write_b32 v93, v95
.LBB0_236:
	s_or_b64 exec, exec, s[20:21]
	v_mul_f32_e32 v95, v133, v133
	v_mul_f32_e32 v100, v135, v135
	v_fmac_f32_e32 v95, v132, v132
	v_fmac_f32_e32 v100, v134, v134
	v_add_f32_e32 v95, v95, v100
	v_mul_f32_e32 v100, v129, v129
	v_fmac_f32_e32 v100, v128, v128
	v_add_f32_e32 v95, v95, v100
	v_mul_f32_e32 v100, v131, v131
	v_fmac_f32_e32 v100, v130, v130
	v_add_f32_e32 v95, v100, v95
	v_mov_b32_e32 v100, v95
	s_nop 1
	v_permlane16_swap_b32_e32 v100, v95
	v_add_f32_e32 v95, v95, v100
	v_mov_b32_e32 v100, v95
	s_nop 1
	v_permlane32_swap_b32_e32 v100, v95
	s_and_saveexec_b64 s[20:21], s[8:9]
	s_cbranch_execz .LBB0_238
	v_add_f32_e32 v95, v95, v100
	ds_write_b32 v93, v95 offset:16
.LBB0_238:
	s_or_b64 exec, exec, s[20:21]
	v_mul_f32_e32 v95, v125, v125
	v_mul_f32_e32 v100, v127, v127
	v_fmac_f32_e32 v95, v124, v124
	v_fmac_f32_e32 v100, v126, v126
	v_add_f32_e32 v95, v95, v100
	v_mul_f32_e32 v100, v121, v121
	v_fmac_f32_e32 v100, v120, v120
	v_add_f32_e32 v95, v95, v100
	v_mul_f32_e32 v100, v123, v123
	v_fmac_f32_e32 v100, v122, v122
	v_add_f32_e32 v95, v100, v95
	v_mov_b32_e32 v100, v95
	s_nop 1
	v_permlane16_swap_b32_e32 v100, v95
	v_add_f32_e32 v95, v95, v100
	v_mov_b32_e32 v100, v95
	s_nop 1
	v_permlane32_swap_b32_e32 v100, v95
	s_and_saveexec_b64 s[20:21], s[8:9]
	s_cbranch_execz .LBB0_240
	v_add_f32_e32 v95, v95, v100
	ds_write_b32 v93, v95 offset:512
.LBB0_240:
	s_or_b64 exec, exec, s[20:21]
	v_mul_f32_e32 v95, v117, v117
	v_mul_f32_e32 v100, v119, v119
	v_fmac_f32_e32 v95, v116, v116
	v_fmac_f32_e32 v100, v118, v118
	v_add_f32_e32 v95, v95, v100
	v_mul_f32_e32 v100, v113, v113
	v_fmac_f32_e32 v100, v112, v112
	v_add_f32_e32 v95, v95, v100
	v_mul_f32_e32 v100, v115, v115
	v_fmac_f32_e32 v100, v114, v114
	v_add_f32_e32 v95, v100, v95
	v_mov_b32_e32 v100, v95
	s_nop 1
	v_permlane16_swap_b32_e32 v100, v95
	v_add_f32_e32 v95, v95, v100
	v_mov_b32_e32 v100, v95
	s_nop 1
	v_permlane32_swap_b32_e32 v100, v95
	s_and_saveexec_b64 s[20:21], s[8:9]
	s_cbranch_execz .LBB0_242
	v_add_f32_e32 v95, v95, v100
	ds_write_b32 v93, v95 offset:528
.LBB0_242:
	s_or_b64 exec, exec, s[20:21]
	v_mul_f32_e32 v95, v97, v97
	v_mul_f32_e32 v100, v99, v99
	v_fmac_f32_e32 v95, v96, v96
	v_fmac_f32_e32 v100, v98, v98
	v_add_f32_e32 v95, v95, v100
	v_mul_f32_e32 v100, v89, v89
	v_fmac_f32_e32 v100, v88, v88
	v_add_f32_e32 v95, v95, v100
	v_mul_f32_e32 v100, v91, v91
	v_fmac_f32_e32 v100, v90, v90
	v_add_f32_e32 v95, v100, v95
	v_mov_b32_e32 v100, v95
	s_nop 1
	v_permlane16_swap_b32_e32 v100, v95
	v_add_f32_e32 v95, v95, v100
	v_mov_b32_e32 v100, v95
	s_nop 1
	v_permlane32_swap_b32_e32 v100, v95
	s_and_saveexec_b64 s[20:21], s[8:9]
	s_cbranch_execz .LBB0_244
	v_add_f32_e32 v95, v95, v100
	ds_write_b32 v93, v95 offset:1024
.LBB0_244:
	s_or_b64 exec, exec, s[20:21]
	v_mul_f32_e32 v95, v85, v85
	v_mul_f32_e32 v100, v87, v87
	v_fmac_f32_e32 v95, v84, v84
	v_fmac_f32_e32 v100, v86, v86
	v_add_f32_e32 v95, v95, v100
	v_mul_f32_e32 v100, v81, v81
	v_fmac_f32_e32 v100, v80, v80
	v_add_f32_e32 v95, v95, v100
	v_mul_f32_e32 v100, v83, v83
	v_fmac_f32_e32 v100, v82, v82
	v_add_f32_e32 v95, v100, v95
	v_mov_b32_e32 v100, v95
	s_nop 1
	v_permlane16_swap_b32_e32 v100, v95
	v_add_f32_e32 v95, v95, v100
	v_mov_b32_e32 v100, v95
	s_nop 1
	v_permlane32_swap_b32_e32 v100, v95
	s_and_saveexec_b64 s[20:21], s[8:9]
	s_cbranch_execz .LBB0_246
	v_add_f32_e32 v95, v95, v100
	ds_write_b32 v93, v95 offset:1040
.LBB0_246:
	s_or_b64 exec, exec, s[20:21]
	v_mul_f32_e32 v95, v77, v77
	v_mul_f32_e32 v100, v79, v79
	v_fmac_f32_e32 v95, v76, v76
	v_fmac_f32_e32 v100, v78, v78
	v_add_f32_e32 v95, v95, v100
	v_mul_f32_e32 v100, v73, v73
	v_fmac_f32_e32 v100, v72, v72
	v_add_f32_e32 v95, v95, v100
	v_mul_f32_e32 v100, v75, v75
	v_fmac_f32_e32 v100, v74, v74
	v_add_f32_e32 v95, v100, v95
	v_mov_b32_e32 v100, v95
	s_nop 1
	v_permlane16_swap_b32_e32 v100, v95
	v_add_f32_e32 v95, v95, v100
	v_mov_b32_e32 v100, v95
	s_nop 1
	v_permlane32_swap_b32_e32 v100, v95
	s_and_saveexec_b64 s[20:21], s[8:9]
	s_cbranch_execz .LBB0_248
	v_add_f32_e32 v95, v95, v100
	ds_write_b32 v93, v95 offset:1536
.LBB0_248:
	s_or_b64 exec, exec, s[20:21]
	v_mul_f32_e32 v95, v69, v69
	v_mul_f32_e32 v100, v71, v71
	v_fmac_f32_e32 v95, v68, v68
	v_fmac_f32_e32 v100, v70, v70
	v_add_f32_e32 v95, v95, v100
	v_mul_f32_e32 v100, v65, v65
	v_fmac_f32_e32 v100, v64, v64
	v_add_f32_e32 v95, v95, v100
	v_mul_f32_e32 v100, v67, v67
	v_fmac_f32_e32 v100, v66, v66
	v_add_f32_e32 v95, v100, v95
	v_mov_b32_e32 v100, v95
	s_nop 1
	v_permlane16_swap_b32_e32 v100, v95
	v_add_f32_e32 v95, v95, v100
	v_mov_b32_e32 v100, v95
	s_nop 1
	v_permlane32_swap_b32_e32 v100, v95
	s_and_saveexec_b64 s[20:21], s[8:9]
	s_cbranch_execz .LBB0_250
	v_add_f32_e32 v95, v95, v100
	ds_write_b32 v93, v95 offset:1552
; __device__ __forceinline__ void head_ss(const f32x4 (&v)[2][2][4][2], float (&tot)[2][4][2], LAS float* X, int wr, int wc, int fr, int fq) {
;     ...
;                 const f32x4 a = v[ai][bj][m][0], b = v[ai][bj][m][1];
;                 float s = (a[0] * a[0] + a[1] * a[1]) + (a[2] * a[2] + a[3] * a[3]) + (b[0] * b[0] + b[1] * b[1]) + (b[2] * b[2] + b[3] * b[3]);
;                 s += __shfl_xor(s, 16); s += __shfl_xor(s, 32);
;                 if (fq == 0) X[((ai * 128 + wr * 64 + m * 16 + fr) * 2 + bj) * 4 + wc] = s;
.LBB0_250:
	s_or_b64 exec, exec, s[20:21]
	v_mul_f32_e32 v95, v61, v61
	v_mul_f32_e32 v100, v63, v63
	v_fmac_f32_e32 v95, v60, v60
	v_fmac_f32_e32 v100, v62, v62
	v_add_f32_e32 v95, v95, v100
	v_mul_f32_e32 v100, v57, v57
	v_fmac_f32_e32 v100, v56, v56
	v_add_f32_e32 v95, v95, v100
	v_mul_f32_e32 v100, v59, v59
	v_fmac_f32_e32 v100, v58, v58
	v_add_f32_e32 v95, v100, v95
	v_mov_b32_e32 v100, v95
	s_nop 1
	v_permlane16_swap_b32_e32 v100, v95
	v_add_f32_e32 v95, v95, v100
	v_mov_b32_e32 v100, v95
	s_nop 1
	v_permlane32_swap_b32_e32 v100, v95
	s_and_saveexec_b64 s[20:21], s[8:9]
	s_cbranch_execz .LBB0_252
	v_add_f32_e32 v95, v95, v100
	ds_write_b32 v93, v95 offset:4096
.LBB0_252:
	s_or_b64 exec, exec, s[20:21]
	v_mul_f32_e32 v95, v53, v53
	v_mul_f32_e32 v100, v55, v55
	v_fmac_f32_e32 v95, v52, v52
	v_fmac_f32_e32 v100, v54, v54
	v_add_f32_e32 v95, v95, v100
	v_mul_f32_e32 v100, v49, v49
	v_fmac_f32_e32 v100, v48, v48
	v_add_f32_e32 v95, v95, v100
	v_mul_f32_e32 v100, v51, v51
	v_fmac_f32_e32 v100, v50, v50
	v_add_f32_e32 v95, v100, v95
	v_mov_b32_e32 v100, v95
	s_nop 1
	v_permlane16_swap_b32_e32 v100, v95
	v_add_f32_e32 v95, v95, v100
	v_mov_b32_e32 v100, v95
	s_nop 1
	v_permlane32_swap_b32_e32 v100, v95
	s_and_saveexec_b64 s[20:21], s[8:9]
	s_cbranch_execz .LBB0_254
	v_add_f32_e32 v95, v95, v100
	ds_write_b32 v93, v95 offset:4112
.LBB0_254:
	s_or_b64 exec, exec, s[20:21]
	v_mul_f32_e32 v95, v45, v45
	v_mul_f32_e32 v100, v47, v47
	v_fmac_f32_e32 v95, v44, v44
	v_fmac_f32_e32 v100, v46, v46
	v_add_f32_e32 v95, v95, v100
	v_mul_f32_e32 v100, v41, v41
	v_fmac_f32_e32 v100, v40, v40
	v_add_f32_e32 v95, v95, v100
	v_mul_f32_e32 v100, v43, v43
	v_fmac_f32_e32 v100, v42, v42
	v_add_f32_e32 v95, v100, v95
	v_mov_b32_e32 v100, v95
	s_nop 1
	v_permlane16_swap_b32_e32 v100, v95
	v_add_f32_e32 v95, v95, v100
	v_mov_b32_e32 v100, v95
	s_nop 1
	v_permlane32_swap_b32_e32 v100, v95
	s_and_saveexec_b64 s[20:21], s[8:9]
	s_cbranch_execz .LBB0_256
	v_add_f32_e32 v95, v95, v100
	ds_write_b32 v93, v95 offset:4608
.LBB0_256:
	s_or_b64 exec, exec, s[20:21]
	v_mul_f32_e32 v95, v37, v37
	v_mul_f32_e32 v100, v39, v39
	v_fmac_f32_e32 v95, v36, v36
	v_fmac_f32_e32 v100, v38, v38
	v_add_f32_e32 v95, v95, v100
	v_mul_f32_e32 v100, v33, v33
	v_fmac_f32_e32 v100, v32, v32
	v_add_f32_e32 v95, v95, v100
	v_mul_f32_e32 v100, v35, v35
	v_fmac_f32_e32 v100, v34, v34
	v_add_f32_e32 v95, v100, v95
	v_mov_b32_e32 v100, v95
	s_nop 1
	v_permlane16_swap_b32_e32 v100, v95
	v_add_f32_e32 v95, v95, v100
	v_mov_b32_e32 v100, v95
	s_nop 1
	v_permlane32_swap_b32_e32 v100, v95
	s_and_saveexec_b64 s[20:21], s[8:9]
	s_cbranch_execz .LBB0_258
	v_add_f32_e32 v95, v95, v100
	ds_write_b32 v93, v95 offset:4624
.LBB0_258:
	s_or_b64 exec, exec, s[20:21]
	v_mul_f32_e32 v95, v29, v29
	v_mul_f32_e32 v100, v31, v31
	v_fmac_f32_e32 v95, v28, v28
	v_fmac_f32_e32 v100, v30, v30
	v_add_f32_e32 v95, v95, v100
	v_mul_f32_e32 v100, v25, v25
	v_fmac_f32_e32 v100, v24, v24
	v_add_f32_e32 v95, v95, v100
	v_mul_f32_e32 v100, v27, v27
	v_fmac_f32_e32 v100, v26, v26
	v_add_f32_e32 v95, v100, v95
	v_mov_b32_e32 v100, v95
	s_nop 1
	v_permlane16_swap_b32_e32 v100, v95
	v_add_f32_e32 v95, v95, v100
	v_mov_b32_e32 v100, v95
	s_nop 1
	v_permlane32_swap_b32_e32 v100, v95
	s_and_saveexec_b64 s[20:21], s[8:9]
	s_cbranch_execz .LBB0_260
	v_add_f32_e32 v95, v95, v100
	ds_write_b32 v93, v95 offset:5120
.LBB0_260:
	s_or_b64 exec, exec, s[20:21]
	v_mul_f32_e32 v95, v21, v21
	v_mul_f32_e32 v100, v23, v23
	v_fmac_f32_e32 v95, v20, v20
	v_fmac_f32_e32 v100, v22, v22
	v_add_f32_e32 v95, v95, v100
	v_mul_f32_e32 v100, v17, v17
	v_fmac_f32_e32 v100, v16, v16
	v_add_f32_e32 v95, v95, v100
	v_mul_f32_e32 v100, v19, v19
	v_fmac_f32_e32 v100, v18, v18
	v_add_f32_e32 v95, v100, v95
	v_mov_b32_e32 v100, v95
	s_nop 1
	v_permlane16_swap_b32_e32 v100, v95
	v_add_f32_e32 v95, v95, v100
	v_mov_b32_e32 v100, v95
	s_nop 1
	v_permlane32_swap_b32_e32 v100, v95
	s_and_saveexec_b64 s[20:21], s[8:9]
	s_cbranch_execz .LBB0_262
	v_add_f32_e32 v95, v95, v100
	ds_write_b32 v93, v95 offset:5136
.LBB0_262:
	s_or_b64 exec, exec, s[20:21]
	v_mul_f32_e32 v95, v13, v13
	v_mul_f32_e32 v100, v15, v15
	v_fmac_f32_e32 v95, v12, v12
	v_fmac_f32_e32 v100, v14, v14
	v_add_f32_e32 v95, v95, v100
	v_mul_f32_e32 v100, v9, v9
	v_fmac_f32_e32 v100, v8, v8
	v_add_f32_e32 v95, v95, v100
	v_mul_f32_e32 v100, v11, v11
	v_fmac_f32_e32 v100, v10, v10
	v_add_f32_e32 v95, v100, v95
	v_mov_b32_e32 v100, v95
	s_nop 1
	v_permlane16_swap_b32_e32 v100, v95
	v_add_f32_e32 v95, v95, v100
	v_mov_b32_e32 v100, v95
	s_nop 1
	v_permlane32_swap_b32_e32 v100, v95
	s_and_saveexec_b64 s[20:21], s[8:9]
	s_cbranch_execz .LBB0_264
	v_add_f32_e32 v95, v95, v100
	ds_write_b32 v93, v95 offset:5632
.LBB0_264:
	s_or_b64 exec, exec, s[20:21]
	v_mul_f32_e32 v95, v5, v5
	v_mul_f32_e32 v100, v7, v7
	v_fmac_f32_e32 v95, v4, v4
	v_fmac_f32_e32 v100, v6, v6
	v_add_f32_e32 v95, v95, v100
	v_mul_f32_e32 v100, v1, v1
	v_fmac_f32_e32 v100, v0, v0
	v_add_f32_e32 v95, v95, v100
	v_mul_f32_e32 v100, v3, v3
	v_fmac_f32_e32 v100, v2, v2
	v_add_f32_e32 v95, v100, v95
	v_mov_b32_e32 v92, v95
	s_nop 1
	v_permlane16_swap_b32_e32 v92, v95
	v_add_f32_e32 v92, v95, v92
	v_mov_b32_e32 v94, v92
	s_nop 1
	v_permlane32_swap_b32_e32 v94, v92
	s_and_saveexec_b64 s[20:21], s[8:9]
	s_cbranch_execz .LBB0_266
	v_add_f32_e32 v92, v92, v94
	ds_write_b32 v93, v92 offset:5648

; __device__ __forceinline__ u32x4 pack8(f32x4 a, f32x4 b) { u32x4 w; w.x = cvtpk(a[0], a[1]); w.y = cvtpk(a[2], a[3]); w.z = cvtpk(b[0], b[1]); w.w = cvtpk(b[2], b[3]); return w; }
; #define FOR_BJ _Pragma("unroll") for (int bj = 0; bj < 2; ++bj)
;     __device__ __forceinline__ void operator()(f32x4 (&acc)[2][2][4][2], const Unit& u, int wr, int wc, int fr, int fq) const {
;         const float* xb = u.pm < NPR / BM ? xp : xs - (size_t)NPR * DM;
; #pragma unroll
;         for (int ai = 0; ai < 2; ++ai) {
;             f32x4 xr[4][2][2];
; #pragma unroll
;             for (int m = 0; m < 4; ++m) FOR_BJ { const unsigned off = (unsigned)(u.pm * BM + ai * HALF + wr * 64 + m * 16 + fr) * DM + u.pn * BM + 128 * bj + 32 * wc + 8 * fq;
;                 xr[m][bj][0] = *(const f32x4*)(xb + off); xr[m][bj][1] = *(const f32x4*)(xb + off + 4); }
; #pragma unroll
;             for (int m = 0; m < 4; ++m) FOR_BJ { const unsigned off = (unsigned)(u.pm * BM + ai * HALF + wr * 64 + m * 16 + fr) * DM + u.pn * BM + 128 * bj + 32 * wc + 8 * fq;
;                 const f32x4 v0 = acc[ai][bj][m][0] + xr[m][bj][0], v1 = acc[ai][bj][m][1] + xr[m][bj][1];
;                 acc[ai][bj][m][0] = v0; acc[ai][bj][m][1] = v1;
;                 *(u32x4*)(HB + off) = pack8(v0, v1); }
.LBB0_759:
	v_readlane_b32 s36, v243, 3
	s_cmpk_lt_i32 s30, 0x80
	v_readlane_b32 s37, v243, 4
	v_readlane_b32 s50, v243, 17
	v_readlane_b32 s51, v243, 18
	v_lshl_add_u32 v142, s30, 8, v152
	v_lshl_or_b32 v136, s10, 8, v154
	s_cselect_b32 s51, s37, s62
	s_cselect_b32 s50, s36, s61
	v_lshl_add_u32 v136, v142, 11, v136
	s_waitcnt vmcnt(0)
	v_lshl_add_u64 v[148:149], v[136:137], 2, s[50:51]
	global_load_dwordx4 v[144:147], v[148:149], off
	global_load_dwordx4 v[160:163], v[148:149], off offset:16
	global_load_dwordx4 v[164:167], v[148:149], off offset:512
	global_load_dwordx4 v[168:171], v[148:149], off offset:528
	v_mov_b32_e32 v149, v137
	v_add_u32_e32 v148, 0x8000, v136
	v_lshl_add_u64 v[150:151], v[148:149], 2, s[50:51]
	global_load_dwordx4 v[172:175], v[150:151], off
	global_load_dwordx4 v[180:183], v[150:151], off offset:16
	global_load_dwordx4 v[184:187], v[150:151], off offset:528
	global_load_dwordx4 v[188:191], v[150:151], off offset:512
	v_mov_b32_e32 v225, v137
	v_add_u32_e32 v224, 0x10000, v136
	v_lshl_add_u64 v[150:151], v[224:225], 2, s[50:51]
	global_load_dwordx4 v[192:195], v[150:151], off
	global_load_dwordx4 v[196:199], v[150:151], off offset:16
	global_load_dwordx4 v[200:203], v[150:151], off offset:512
	global_load_dwordx4 v[204:207], v[150:151], off offset:528
	v_mov_b32_e32 v227, v137
	v_add_u32_e32 v226, 0x18000, v136
	v_lshl_add_u64 v[150:151], v[226:227], 2, s[50:51]
	global_load_dwordx4 v[208:211], v[150:151], off
	global_load_dwordx4 v[212:215], v[150:151], off offset:16
	global_load_dwordx4 v[216:219], v[150:151], off offset:512
	global_load_dwordx4 v[220:223], v[150:151], off offset:528
	v_mov_b32_e32 v151, v137
	v_add_u32_e32 v150, 0x8080, v136
	v_lshl_add_u64 v[236:237], v[148:149], 1, s[88:89]
	v_lshl_add_u64 v[238:239], v[150:151], 1, s[88:89]
	v_mov_b32_e32 v229, v137
	v_or_b32_e32 v228, 0x80, v136
	v_lshl_add_u64 v[234:235], v[136:137], 1, s[88:89]
	v_lshl_add_u64 v[228:229], v[228:229], 1, s[88:89]
	v_mov_b32_e32 v231, v137
	v_add_u32_e32 v230, 0x10080, v136
	v_mov_b32_e32 v233, v137
	v_add_u32_e32 v232, 0x18080, v136
	v_readlane_b32 s46, v243, 13
	v_readlane_b32 s47, v243, 14
	v_readlane_b32 s38, v243, 5
	v_readlane_b32 s39, v243, 6
	v_readlane_b32 s40, v243, 7
	v_readlane_b32 s41, v243, 8
	v_readlane_b32 s42, v243, 9
	v_readlane_b32 s43, v243, 10
	v_readlane_b32 s44, v243, 11
	v_readlane_b32 s45, v243, 12
	v_readlane_b32 s48, v243, 15
	v_readlane_b32 s49, v243, 16
	s_waitcnt vmcnt(0)
	v_pk_add_f32 v[148:149], v[126:127], v[146:147]
	v_pk_add_f32 v[150:151], v[124:125], v[144:145]
	v_pk_add_f32 v[144:145], v[122:123], v[162:163]
	v_pk_add_f32 v[146:147], v[120:121], v[160:161]
	v_pk_add_f32 v[118:119], v[118:119], v[174:175]
	v_pk_add_f32 v[116:117], v[116:117], v[172:173]
	v_pk_add_f32 v[114:115], v[114:115], v[182:183]
	v_pk_add_f32 v[112:113], v[112:113], v[180:181]
	v_pk_add_f32 v[124:125], v[110:111], v[166:167]
	v_pk_add_f32 v[126:127], v[108:109], v[164:165]
	v_pk_add_f32 v[120:121], v[106:107], v[170:171]
	v_pk_add_f32 v[122:123], v[104:105], v[168:169]
	v_cvt_pk_bf16_f32 v160, v150, v151
	v_cvt_pk_bf16_f32 v161, v148, v149
	v_cvt_pk_bf16_f32 v162, v146, v147
	v_cvt_pk_bf16_f32 v163, v144, v145
	v_pk_add_f32 v[108:109], v[94:95], v[190:191]
	v_pk_add_f32 v[110:111], v[92:93], v[188:189]
	v_pk_add_f32 v[104:105], v[90:91], v[186:187]
	v_pk_add_f32 v[106:107], v[88:89], v[184:185]
	v_pk_add_f32 v[90:91], v[102:103], v[194:195]
	v_pk_add_f32 v[94:95], v[100:101], v[192:193]
	v_pk_add_f32 v[88:89], v[98:99], v[198:199]
	v_pk_add_f32 v[92:93], v[96:97], v[196:197]
	v_cvt_pk_bf16_f32 v96, v116, v117
	v_cvt_pk_bf16_f32 v97, v118, v119
	v_cvt_pk_bf16_f32 v98, v112, v113
	v_cvt_pk_bf16_f32 v99, v114, v115
	v_cvt_pk_bf16_f32 v164, v126, v127
	v_cvt_pk_bf16_f32 v165, v124, v125
	v_cvt_pk_bf16_f32 v166, v122, v123
	v_cvt_pk_bf16_f32 v167, v120, v121
	global_store_dwordx4 v[234:235], v[160:163], off
	global_store_dwordx4 v[228:229], v[164:167], off
	v_cvt_pk_bf16_f32 v100, v110, v111
	v_cvt_pk_bf16_f32 v101, v108, v109
	v_cvt_pk_bf16_f32 v102, v106, v107
	v_cvt_pk_bf16_f32 v103, v104, v105
	v_cvt_pk_bf16_f32 v160, v94, v95
	v_cvt_pk_bf16_f32 v161, v90, v91
	global_store_dwordx4 v[236:237], v[96:99], off
	global_store_dwordx4 v[238:239], v[100:103], off
	v_cvt_pk_bf16_f32 v162, v92, v93
	v_cvt_pk_bf16_f32 v163, v88, v89
	v_lshl_add_u64 v[96:97], v[224:225], 1, s[88:89]
	global_store_dwordx4 v[96:97], v[160:163], off
	v_pk_add_f32 v[96:97], v[82:83], v[202:203]
	v_pk_add_f32 v[100:101], v[80:81], v[200:201]
	v_pk_add_f32 v[80:81], v[74:75], v[206:207]
	v_pk_add_f32 v[98:99], v[72:73], v[204:205]
	v_cvt_pk_bf16_f32 v72, v100, v101
	v_cvt_pk_bf16_f32 v73, v96, v97
	v_cvt_pk_bf16_f32 v74, v98, v99
	v_cvt_pk_bf16_f32 v75, v80, v81
	v_lshl_add_u64 v[82:83], v[230:231], 1, s[88:89]
	global_store_dwordx4 v[82:83], v[72:75], off
	v_pk_add_f32 v[82:83], v[84:85], v[208:209]
	v_pk_add_f32 v[76:77], v[76:77], v[212:213]
	v_pk_add_f32 v[74:75], v[86:87], v[210:211]
	v_pk_add_f32 v[72:73], v[78:79], v[214:215]
	v_cvt_pk_bf16_f32 v84, v82, v83
	v_cvt_pk_bf16_f32 v85, v74, v75
	v_cvt_pk_bf16_f32 v86, v76, v77
	v_cvt_pk_bf16_f32 v87, v72, v73
	v_lshl_add_u64 v[78:79], v[226:227], 1, s[88:89]
	v_pk_add_f32 v[70:71], v[70:71], v[218:219]
	v_pk_add_f32 v[68:69], v[68:69], v[216:217]
	v_pk_add_f32 v[66:67], v[66:67], v[222:223]
	v_pk_add_f32 v[64:65], v[64:65], v[220:221]
	global_store_dwordx4 v[78:79], v[84:87], off
	v_lshl_add_u64 v[78:79], v[232:233], 1, s[88:89]
	v_add_u32_e32 v224, 0x48000, v136
	v_cvt_pk_bf16_f32 v84, v68, v69
	v_cvt_pk_bf16_f32 v85, v70, v71
	v_cvt_pk_bf16_f32 v86, v64, v65
	v_cvt_pk_bf16_f32 v87, v66, v67
; __device__ __forceinline__ u32x4 pack8(f32x4 a, f32x4 b) { u32x4 w; w.x = cvtpk(a[0], a[1]); w.y = cvtpk(a[2], a[3]); w.z = cvtpk(b[0], b[1]); w.w = cvtpk(b[2], b[3]); return w; }
; #define FOR_BJ _Pragma("unroll") for (int bj = 0; bj < 2; ++bj)
; __device__ __forceinline__ void head_ss(const f32x4 (&v)[2][2][4][2], float (&tot)[2][4][2], LAS float* X, int wr, int wc, int fr, int fq) {
;     ...
;                 const f32x4 a = v[ai][bj][m][0], b = v[ai][bj][m][1];
;                 float s = (a[0] * a[0] + a[1] * a[1]) + (a[2] * a[2] + a[3] * a[3]) + (b[0] * b[0] + b[1] * b[1]) + (b[2] * b[2] + b[3] * b[3]);
;                 s += __shfl_xor(s, 16); s += __shfl_xor(s, 32);
;                 if (fq == 0) X[((ai * 128 + wr * 64 + m * 16 + fr) * 2 + bj) * 4 + wc] = s;
;     __device__ __forceinline__ void operator()(f32x4 (&acc)[2][2][4][2], const Unit& u, int wr, int wc, int fr, int fq) const {
;     ...
;             for (int m = 0; m < 4; ++m) FOR_BJ { const unsigned off = (unsigned)(u.pm * BM + ai * HALF + wr * 64 + m * 16 + fr) * DM + u.pn * BM + 128 * bj + 32 * wc + 8 * fq;
;                 const f32x4 v0 = acc[ai][bj][m][0] + xr[m][bj][0], v1 = acc[ai][bj][m][1] + xr[m][bj][1];
;                 acc[ai][bj][m][0] = v0; acc[ai][bj][m][1] = v1;
;                 *(u32x4*)(HB + off) = pack8(v0, v1); }
;             asm volatile("" ::: "memory");
	global_store_dwordx4 v[78:79], v[84:87], off
	v_add_u32_e32 v78, 0x40000, v136
	v_mov_b32_e32 v79, v137
	v_lshl_add_u64 v[102:103], v[78:79], 2, s[50:51]
	global_load_dwordx4 v[84:87], v[102:103], off
	global_load_dwordx4 v[160:163], v[102:103], off offset:16
	global_load_dwordx4 v[164:167], v[102:103], off offset:512
	global_load_dwordx4 v[168:171], v[102:103], off offset:528
	v_lshl_add_u64 v[102:103], v[224:225], 2, s[50:51]
	global_load_dwordx4 v[172:175], v[102:103], off
	global_load_dwordx4 v[180:183], v[102:103], off offset:16
	global_load_dwordx4 v[184:187], v[102:103], off offset:512
	global_load_dwordx4 v[188:191], v[102:103], off offset:528
	v_add_u32_e32 v226, 0x50000, v136
	v_lshl_add_u64 v[102:103], v[226:227], 2, s[50:51]
	global_load_dwordx4 v[192:195], v[102:103], off
	global_load_dwordx4 v[196:199], v[102:103], off offset:16
	global_load_dwordx4 v[200:203], v[102:103], off offset:512
	global_load_dwordx4 v[204:207], v[102:103], off offset:528
	v_mov_b32_e32 v229, v137
	v_add_u32_e32 v228, 0x58000, v136
	v_lshl_add_u64 v[102:103], v[228:229], 2, s[50:51]
	global_load_dwordx4 v[208:211], v[102:103], off
	global_load_dwordx4 v[212:215], v[102:103], off offset:16
	global_load_dwordx4 v[216:219], v[102:103], off offset:512
	global_load_dwordx4 v[220:223], v[102:103], off offset:528
	v_lshl_add_u64 v[236:237], v[78:79], 1, s[88:89]
	v_add_u32_e32 v230, 0x40080, v136
	v_add_u32_e32 v232, 0x48080, v136
	v_mov_b32_e32 v235, v137
	v_add_u32_e32 v234, 0x50080, v136
	v_add_u32_e32 v136, 0x58080, v136
	s_waitcnt vmcnt(15)
	v_pk_add_f32 v[86:87], v[62:63], v[86:87]
	v_pk_add_f32 v[102:103], v[60:61], v[84:85]
	s_waitcnt vmcnt(14)
	v_pk_add_f32 v[78:79], v[58:59], v[162:163]
	v_pk_add_f32 v[84:85], v[56:57], v[160:161]
	s_waitcnt vmcnt(13)
	v_pk_add_f32 v[54:55], v[54:55], v[166:167]
	v_pk_add_f32 v[62:63], v[52:53], v[164:165]
	s_waitcnt vmcnt(12)
	v_pk_add_f32 v[52:53], v[46:47], v[170:171]
	v_pk_add_f32 v[58:59], v[44:45], v[168:169]
	v_cvt_pk_bf16_f32 v44, v102, v103
	v_cvt_pk_bf16_f32 v45, v86, v87
	v_cvt_pk_bf16_f32 v46, v84, v85
	v_cvt_pk_bf16_f32 v47, v78, v79
	global_store_dwordx4 v[236:237], v[44:47], off
	v_lshl_add_u64 v[56:57], v[230:231], 1, s[88:89]
	s_waitcnt vmcnt(12)
	v_pk_add_f32 v[50:51], v[50:51], v[174:175]
	v_cvt_pk_bf16_f32 v44, v62, v63
	v_cvt_pk_bf16_f32 v45, v54, v55
	v_cvt_pk_bf16_f32 v46, v58, v59
	v_cvt_pk_bf16_f32 v47, v52, v53
	global_store_dwordx4 v[56:57], v[44:47], off
	v_pk_add_f32 v[60:61], v[48:49], v[172:173]
	s_waitcnt vmcnt(12)
	v_pk_add_f32 v[56:57], v[40:41], v[180:181]
	v_pk_add_f32 v[46:47], v[42:43], v[182:183]
	v_cvt_pk_bf16_f32 v40, v60, v61
	v_cvt_pk_bf16_f32 v41, v50, v51
	v_cvt_pk_bf16_f32 v42, v56, v57
	v_cvt_pk_bf16_f32 v43, v46, v47
	v_lshl_add_u64 v[44:45], v[224:225], 1, s[88:89]
	global_store_dwordx4 v[44:45], v[40:43], off
	s_waitcnt vmcnt(12)
	v_pk_add_f32 v[48:49], v[32:33], v[184:185]
	s_waitcnt vmcnt(11)
	v_pk_add_f32 v[44:45], v[24:25], v[188:189]
	v_pk_add_f32 v[42:43], v[34:35], v[186:187]
	v_pk_add_f32 v[40:41], v[26:27], v[190:191]
	v_cvt_pk_bf16_f32 v24, v48, v49
	v_cvt_pk_bf16_f32 v25, v42, v43
	v_cvt_pk_bf16_f32 v26, v44, v45
	v_cvt_pk_bf16_f32 v27, v40, v41
	v_lshl_add_u64 v[32:33], v[232:233], 1, s[88:89]
	global_store_dwordx4 v[32:33], v[24:27], off
	s_waitcnt vmcnt(11)
	v_pk_add_f32 v[32:33], v[38:39], v[194:195]
	v_pk_add_f32 v[36:37], v[36:37], v[192:193]
	s_waitcnt vmcnt(10)
	v_pk_add_f32 v[30:31], v[30:31], v[198:199]
	v_pk_add_f32 v[34:35], v[28:29], v[196:197]
	v_cvt_pk_bf16_f32 v24, v36, v37
	v_cvt_pk_bf16_f32 v25, v32, v33
	v_cvt_pk_bf16_f32 v26, v34, v35
	v_cvt_pk_bf16_f32 v27, v30, v31
	v_lshl_add_u64 v[28:29], v[226:227], 1, s[88:89]
	global_store_dwordx4 v[28:29], v[24:27], off
	s_waitcnt vmcnt(10)
	v_pk_add_f32 v[28:29], v[16:17], v[200:201]
	s_waitcnt vmcnt(9)
	v_pk_add_f32 v[16:17], v[10:11], v[206:207]
	v_pk_add_f32 v[24:25], v[18:19], v[202:203]
	v_pk_add_f32 v[26:27], v[8:9], v[204:205]
	v_cvt_pk_bf16_f32 v8, v28, v29
	v_cvt_pk_bf16_f32 v9, v24, v25
	v_cvt_pk_bf16_f32 v10, v26, v27
	v_cvt_pk_bf16_f32 v11, v16, v17
	v_lshl_add_u64 v[18:19], v[234:235], 1, s[88:89]
	global_store_dwordx4 v[18:19], v[8:11], off
	s_waitcnt vmcnt(9)
	v_pk_add_f32 v[18:19], v[20:21], v[208:209]
	s_waitcnt vmcnt(8)
	v_pk_add_f32 v[12:13], v[12:13], v[212:213]
	v_pk_add_f32 v[10:11], v[22:23], v[210:211]
	v_pk_add_f32 v[8:9], v[14:15], v[214:215]
	v_cvt_pk_bf16_f32 v20, v18, v19
	v_cvt_pk_bf16_f32 v21, v10, v11
	v_cvt_pk_bf16_f32 v22, v12, v13
	v_cvt_pk_bf16_f32 v23, v8, v9
	v_lshl_add_u64 v[14:15], v[228:229], 1, s[88:89]
	s_waitcnt vmcnt(7)
	v_pk_add_f32 v[6:7], v[6:7], v[218:219]
	v_pk_add_f32 v[4:5], v[4:5], v[216:217]
	s_waitcnt vmcnt(6)
	v_pk_add_f32 v[2:3], v[2:3], v[222:223]
	v_pk_add_f32 v[0:1], v[0:1], v[220:221]
	global_store_dwordx4 v[14:15], v[20:23], off
	v_lshl_add_u64 v[14:15], v[136:137], 1, s[88:89]
	s_nop 0
	v_cvt_pk_bf16_f32 v20, v4, v5
	v_cvt_pk_bf16_f32 v21, v6, v7
	v_cvt_pk_bf16_f32 v22, v0, v1
	v_cvt_pk_bf16_f32 v23, v2, v3
	global_store_dwordx4 v[14:15], v[20:23], off
	v_and_b32_e32 v15, 64, v159
	v_xor_b32_e32 v14, 16, v159
	v_mul_f32_e32 v20, v151, v151
	v_mul_f32_e32 v21, v149, v149
	v_fmac_f32_e32 v20, v150, v150
	v_fmac_f32_e32 v21, v148, v148
	v_add_f32_e32 v20, v20, v21
	v_mul_f32_e32 v21, v147, v147
	v_add_u32_e32 v15, 64, v15
	v_fmac_f32_e32 v21, v146, v146
	v_cmp_lt_i32_e32 vcc, v14, v15
	v_add_f32_e32 v20, v20, v21
	v_mul_f32_e32 v21, v145, v145
	v_cndmask_b32_e32 v14, v159, v14, vcc
	v_fmac_f32_e32 v21, v144, v144
	v_lshlrev_b32_e32 v14, 2, v14
	v_add_f32_e32 v21, v21, v20
	v_mov_b32_e32 v22, v21
	s_nop 1
	v_permlane16_swap_b32_e32 v22, v21
	v_xor_b32_e32 v20, 32, v159
	v_cmp_lt_i32_e32 vcc, v20, v15
	v_add_f32_e32 v21, v21, v22
	v_cndmask_b32_e32 v15, v159, v20, vcc
	v_lshlrev_b32_e32 v20, 2, v15
	v_mov_b32_e32 v22, v21
	s_nop 1
	v_permlane32_swap_b32_e32 v22, v21
	v_add_u32_e32 v15, s64, v155
	s_and_saveexec_b64 s[46:47], s[0:1]
	v_readlane_b32 s96, v243, 61
	v_readlane_b32 s97, v243, 62
	s_cbranch_execz .LBB0_761
	v_add_f32_e32 v21, v21, v22
	ds_write_b32 v15, v21
; __device__ __forceinline__ void head_ss(const f32x4 (&v)[2][2][4][2], float (&tot)[2][4][2], LAS float* X, int wr, int wc, int fr, int fq) {
;     ...
;                 const f32x4 a = v[ai][bj][m][0], b = v[ai][bj][m][1];
;                 float s = (a[0] * a[0] + a[1] * a[1]) + (a[2] * a[2] + a[3] * a[3]) + (b[0] * b[0] + b[1] * b[1]) + (b[2] * b[2] + b[3] * b[3]);
;                 s += __shfl_xor(s, 16); s += __shfl_xor(s, 32);
;                 if (fq == 0) X[((ai * 128 + wr * 64 + m * 16 + fr) * 2 + bj) * 4 + wc] = s;
.LBB0_761:
	s_or_b64 exec, exec, s[46:47]
	v_mul_f32_e32 v21, v127, v127
	v_mul_f32_e32 v22, v125, v125
	v_fmac_f32_e32 v21, v126, v126
	v_fmac_f32_e32 v22, v124, v124
	v_add_f32_e32 v21, v21, v22
	v_mul_f32_e32 v22, v123, v123
	v_fmac_f32_e32 v22, v122, v122
	v_add_f32_e32 v21, v21, v22
	v_mul_f32_e32 v22, v121, v121
	v_fmac_f32_e32 v22, v120, v120
	v_add_f32_e32 v21, v22, v21
	v_mov_b32_e32 v22, v21
	s_nop 1
	v_permlane16_swap_b32_e32 v22, v21
	v_add_f32_e32 v21, v21, v22
	v_mov_b32_e32 v22, v21
	s_nop 1
	v_permlane32_swap_b32_e32 v22, v21
	s_and_saveexec_b64 s[46:47], s[0:1]
	s_cbranch_execz .LBB0_763
	v_add_f32_e32 v21, v21, v22
	ds_write_b32 v15, v21 offset:16
.LBB0_763:
	s_or_b64 exec, exec, s[46:47]
	v_mul_f32_e32 v21, v117, v117
	v_mul_f32_e32 v22, v119, v119
	v_fmac_f32_e32 v21, v116, v116
	v_fmac_f32_e32 v22, v118, v118
	v_add_f32_e32 v21, v21, v22
	v_mul_f32_e32 v22, v113, v113
	v_fmac_f32_e32 v22, v112, v112
	v_add_f32_e32 v21, v21, v22
	v_mul_f32_e32 v22, v115, v115
	v_fmac_f32_e32 v22, v114, v114
	v_add_f32_e32 v21, v22, v21
	v_mov_b32_e32 v22, v21
	s_nop 1
	v_permlane16_swap_b32_e32 v22, v21
	v_add_f32_e32 v21, v21, v22
	v_mov_b32_e32 v22, v21
	s_nop 1
	v_permlane32_swap_b32_e32 v22, v21
	s_and_saveexec_b64 s[46:47], s[0:1]
	s_cbranch_execz .LBB0_765
	v_add_f32_e32 v21, v21, v22
	ds_write_b32 v15, v21 offset:512
.LBB0_765:
	s_or_b64 exec, exec, s[46:47]
	v_mul_f32_e32 v21, v111, v111
	v_mul_f32_e32 v22, v109, v109
	v_fmac_f32_e32 v21, v110, v110
	v_fmac_f32_e32 v22, v108, v108
	v_add_f32_e32 v21, v21, v22
	v_mul_f32_e32 v22, v107, v107
	v_fmac_f32_e32 v22, v106, v106
	v_add_f32_e32 v21, v21, v22
	v_mul_f32_e32 v22, v105, v105
	v_fmac_f32_e32 v22, v104, v104
	v_add_f32_e32 v21, v22, v21
	v_mov_b32_e32 v22, v21
	s_nop 1
	v_permlane16_swap_b32_e32 v22, v21
	v_add_f32_e32 v21, v21, v22
	v_mov_b32_e32 v22, v21
	s_nop 1
	v_permlane32_swap_b32_e32 v22, v21
	s_and_saveexec_b64 s[46:47], s[0:1]
	s_cbranch_execz .LBB0_767
	v_add_f32_e32 v21, v21, v22
	ds_write_b32 v15, v21 offset:528
.LBB0_767:
	s_or_b64 exec, exec, s[46:47]
	v_mul_f32_e32 v21, v95, v95
	v_mul_f32_e32 v22, v91, v91
	v_fmac_f32_e32 v21, v94, v94
	v_fmac_f32_e32 v22, v90, v90
	v_add_f32_e32 v21, v21, v22
	v_mul_f32_e32 v22, v93, v93
	v_fmac_f32_e32 v22, v92, v92
	v_add_f32_e32 v21, v21, v22
	v_mul_f32_e32 v22, v89, v89
	v_fmac_f32_e32 v22, v88, v88
	v_add_f32_e32 v21, v22, v21
	v_mov_b32_e32 v22, v21
	s_nop 1
	v_permlane16_swap_b32_e32 v22, v21
	v_add_f32_e32 v21, v21, v22
	v_mov_b32_e32 v22, v21
	s_nop 1
	v_permlane32_swap_b32_e32 v22, v21
	s_and_saveexec_b64 s[46:47], s[0:1]
	s_cbranch_execz .LBB0_769
	v_add_f32_e32 v21, v21, v22
	ds_write_b32 v15, v21 offset:1024
.LBB0_769:
	s_or_b64 exec, exec, s[46:47]
	v_mul_f32_e32 v21, v101, v101
	v_mul_f32_e32 v22, v97, v97
	v_fmac_f32_e32 v21, v100, v100
	v_fmac_f32_e32 v22, v96, v96
	v_add_f32_e32 v21, v21, v22
	v_mul_f32_e32 v22, v99, v99
	v_fmac_f32_e32 v22, v98, v98
	v_add_f32_e32 v21, v21, v22
	v_mul_f32_e32 v22, v81, v81
	v_fmac_f32_e32 v22, v80, v80
	v_add_f32_e32 v21, v22, v21
	v_mov_b32_e32 v22, v21
	s_nop 1
	v_permlane16_swap_b32_e32 v22, v21
	v_add_f32_e32 v21, v21, v22
	v_mov_b32_e32 v22, v21
	s_nop 1
	v_permlane32_swap_b32_e32 v22, v21
	s_and_saveexec_b64 s[46:47], s[0:1]
	s_cbranch_execz .LBB0_771
	v_add_f32_e32 v21, v21, v22
	ds_write_b32 v15, v21 offset:1040
.LBB0_771:
	s_or_b64 exec, exec, s[46:47]
	v_mul_f32_e32 v21, v83, v83
	v_mul_f32_e32 v22, v75, v75
	v_fmac_f32_e32 v21, v82, v82
	v_fmac_f32_e32 v22, v74, v74
	v_add_f32_e32 v21, v21, v22
	v_mul_f32_e32 v22, v77, v77
	v_fmac_f32_e32 v22, v76, v76
	v_add_f32_e32 v21, v21, v22
	v_mul_f32_e32 v22, v73, v73
	v_fmac_f32_e32 v22, v72, v72
	v_add_f32_e32 v21, v22, v21
	v_mov_b32_e32 v22, v21
	s_nop 1
	v_permlane16_swap_b32_e32 v22, v21
	v_add_f32_e32 v21, v21, v22
	v_mov_b32_e32 v22, v21
	s_nop 1
	v_permlane32_swap_b32_e32 v22, v21
	s_and_saveexec_b64 s[46:47], s[0:1]
	s_cbranch_execz .LBB0_773
	v_add_f32_e32 v21, v21, v22
	ds_write_b32 v15, v21 offset:1536
.LBB0_773:
	s_or_b64 exec, exec, s[46:47]
	v_mul_f32_e32 v21, v69, v69
	v_mul_f32_e32 v22, v71, v71
	v_fmac_f32_e32 v21, v68, v68
	v_fmac_f32_e32 v22, v70, v70
	v_add_f32_e32 v21, v21, v22
	v_mul_f32_e32 v22, v65, v65
	v_fmac_f32_e32 v22, v64, v64
	v_add_f32_e32 v21, v21, v22
	v_mul_f32_e32 v22, v67, v67
	v_fmac_f32_e32 v22, v66, v66
	v_add_f32_e32 v21, v22, v21
	v_mov_b32_e32 v22, v21
	s_nop 1
	v_permlane16_swap_b32_e32 v22, v21
	v_add_f32_e32 v21, v21, v22
	v_mov_b32_e32 v22, v21
	s_nop 1
	v_permlane32_swap_b32_e32 v22, v21
	s_and_saveexec_b64 s[46:47], s[0:1]
	s_cbranch_execz .LBB0_775
	v_add_f32_e32 v21, v21, v22
	ds_write_b32 v15, v21 offset:1552
; __device__ __forceinline__ void head_ss(const f32x4 (&v)[2][2][4][2], float (&tot)[2][4][2], LAS float* X, int wr, int wc, int fr, int fq) {
;     ...
;                 const f32x4 a = v[ai][bj][m][0], b = v[ai][bj][m][1];
;                 float s = (a[0] * a[0] + a[1] * a[1]) + (a[2] * a[2] + a[3] * a[3]) + (b[0] * b[0] + b[1] * b[1]) + (b[2] * b[2] + b[3] * b[3]);
;                 s += __shfl_xor(s, 16); s += __shfl_xor(s, 32);
;                 if (fq == 0) X[((ai * 128 + wr * 64 + m * 16 + fr) * 2 + bj) * 4 + wc] = s;
.LBB0_775:
	s_or_b64 exec, exec, s[46:47]
	v_mul_f32_e32 v21, v103, v103
	v_mul_f32_e32 v22, v87, v87
	v_fmac_f32_e32 v21, v102, v102
	v_fmac_f32_e32 v22, v86, v86
	v_add_f32_e32 v21, v21, v22
	v_mul_f32_e32 v22, v85, v85
	v_fmac_f32_e32 v22, v84, v84
	v_add_f32_e32 v21, v21, v22
	v_mul_f32_e32 v22, v79, v79
	v_fmac_f32_e32 v22, v78, v78
	v_add_f32_e32 v21, v22, v21
	v_mov_b32_e32 v22, v21
	s_nop 1
	v_permlane16_swap_b32_e32 v22, v21
	v_add_f32_e32 v21, v21, v22
	v_mov_b32_e32 v22, v21
	s_nop 1
	v_permlane32_swap_b32_e32 v22, v21
	s_and_saveexec_b64 s[46:47], s[0:1]
	s_cbranch_execz .LBB0_777
	v_add_f32_e32 v21, v21, v22
	ds_write_b32 v15, v21 offset:4096
.LBB0_777:
	s_or_b64 exec, exec, s[46:47]
	v_mul_f32_e32 v21, v63, v63
	v_mul_f32_e32 v22, v55, v55
	v_fmac_f32_e32 v21, v62, v62
	v_fmac_f32_e32 v22, v54, v54
	v_add_f32_e32 v21, v21, v22
	v_mul_f32_e32 v22, v59, v59
	v_fmac_f32_e32 v22, v58, v58
	v_add_f32_e32 v21, v21, v22
	v_mul_f32_e32 v22, v53, v53
	v_fmac_f32_e32 v22, v52, v52
	v_add_f32_e32 v21, v22, v21
	v_mov_b32_e32 v22, v21
	s_nop 1
	v_permlane16_swap_b32_e32 v22, v21
	v_add_f32_e32 v21, v21, v22
	v_mov_b32_e32 v22, v21
	s_nop 1
	v_permlane32_swap_b32_e32 v22, v21
	s_and_saveexec_b64 s[46:47], s[0:1]
	s_cbranch_execz .LBB0_779
	v_add_f32_e32 v21, v21, v22
	ds_write_b32 v15, v21 offset:4112
.LBB0_779:
	s_or_b64 exec, exec, s[46:47]
	v_mul_f32_e32 v21, v61, v61
	v_mul_f32_e32 v22, v51, v51
	v_fmac_f32_e32 v21, v60, v60
	v_fmac_f32_e32 v22, v50, v50
	v_add_f32_e32 v21, v21, v22
	v_mul_f32_e32 v22, v57, v57
	v_fmac_f32_e32 v22, v56, v56
	v_add_f32_e32 v21, v21, v22
	v_mul_f32_e32 v22, v47, v47
	v_fmac_f32_e32 v22, v46, v46
	v_add_f32_e32 v21, v22, v21
	v_mov_b32_e32 v22, v21
	s_nop 1
	v_permlane16_swap_b32_e32 v22, v21
	v_add_f32_e32 v21, v21, v22
	v_mov_b32_e32 v22, v21
	s_nop 1
	v_permlane32_swap_b32_e32 v22, v21
	s_and_saveexec_b64 s[46:47], s[0:1]
	s_cbranch_execz .LBB0_781
	v_add_f32_e32 v21, v21, v22
	ds_write_b32 v15, v21 offset:4608
.LBB0_781:
	s_or_b64 exec, exec, s[46:47]
	v_mul_f32_e32 v21, v49, v49
	v_mul_f32_e32 v22, v43, v43
	v_fmac_f32_e32 v21, v48, v48
	v_fmac_f32_e32 v22, v42, v42
	v_add_f32_e32 v21, v21, v22
	v_mul_f32_e32 v22, v45, v45
	v_fmac_f32_e32 v22, v44, v44
	v_add_f32_e32 v21, v21, v22
	v_mul_f32_e32 v22, v41, v41
	v_fmac_f32_e32 v22, v40, v40
	v_add_f32_e32 v21, v22, v21
	v_mov_b32_e32 v22, v21
	s_nop 1
	v_permlane16_swap_b32_e32 v22, v21
	v_add_f32_e32 v21, v21, v22
	v_mov_b32_e32 v22, v21
	s_nop 1
	v_permlane32_swap_b32_e32 v22, v21
	s_and_saveexec_b64 s[46:47], s[0:1]
	s_cbranch_execz .LBB0_783
	v_add_f32_e32 v21, v21, v22
	ds_write_b32 v15, v21 offset:4624
.LBB0_783:
	s_or_b64 exec, exec, s[46:47]
	v_mul_f32_e32 v21, v37, v37
	v_mul_f32_e32 v22, v33, v33
	v_fmac_f32_e32 v21, v36, v36
	v_fmac_f32_e32 v22, v32, v32
	v_add_f32_e32 v21, v21, v22
	v_mul_f32_e32 v22, v35, v35
	v_fmac_f32_e32 v22, v34, v34
	v_add_f32_e32 v21, v21, v22
	v_mul_f32_e32 v22, v31, v31
	v_fmac_f32_e32 v22, v30, v30
	v_add_f32_e32 v21, v22, v21
	v_mov_b32_e32 v22, v21
	s_nop 1
	v_permlane16_swap_b32_e32 v22, v21
	v_add_f32_e32 v21, v21, v22
	v_mov_b32_e32 v22, v21
	s_nop 1
	v_permlane32_swap_b32_e32 v22, v21
	s_and_saveexec_b64 s[46:47], s[0:1]
	s_cbranch_execz .LBB0_785
	v_add_f32_e32 v21, v21, v22
	ds_write_b32 v15, v21 offset:5120
.LBB0_785:
	s_or_b64 exec, exec, s[46:47]
	v_mul_f32_e32 v21, v29, v29
	v_mul_f32_e32 v22, v25, v25
	v_fmac_f32_e32 v21, v28, v28
	v_fmac_f32_e32 v22, v24, v24
	v_add_f32_e32 v21, v21, v22
	v_mul_f32_e32 v22, v27, v27
	v_fmac_f32_e32 v22, v26, v26
	v_mul_f32_e32 v17, v17, v17
	v_add_f32_e32 v21, v21, v22
	v_fmac_f32_e32 v17, v16, v16
	v_add_f32_e32 v16, v17, v21
	v_mov_b32_e32 v17, v16
	s_nop 1
	v_permlane16_swap_b32_e32 v17, v16
	v_add_f32_e32 v16, v16, v17
	v_mov_b32_e32 v17, v16
	s_nop 1
	v_permlane32_swap_b32_e32 v17, v16
	s_and_saveexec_b64 s[46:47], s[0:1]
	s_cbranch_execz .LBB0_787
	v_add_f32_e32 v16, v16, v17
	ds_write_b32 v15, v16 offset:5136
.LBB0_787:
	s_or_b64 exec, exec, s[46:47]
	v_mul_f32_e32 v16, v19, v19
	v_mul_f32_e32 v11, v11, v11
	v_fmac_f32_e32 v16, v18, v18
	v_fmac_f32_e32 v11, v10, v10
	v_add_f32_e32 v10, v16, v11
	v_mul_f32_e32 v11, v13, v13
	v_fmac_f32_e32 v11, v12, v12
	v_mul_f32_e32 v9, v9, v9
	v_add_f32_e32 v10, v10, v11
	v_fmac_f32_e32 v9, v8, v8
	v_add_f32_e32 v8, v9, v10
	v_mov_b32_e32 v9, v8
	s_nop 1
	v_permlane16_swap_b32_e32 v9, v8
	v_add_f32_e32 v8, v8, v9
	v_mov_b32_e32 v9, v8
	s_nop 1
	v_permlane32_swap_b32_e32 v9, v8
	s_and_saveexec_b64 s[46:47], s[0:1]
	s_cbranch_execz .LBB0_789
	v_add_f32_e32 v8, v8, v9
	ds_write_b32 v15, v8 offset:5632
.LBB0_789:
	s_or_b64 exec, exec, s[46:47]
	v_mul_f32_e32 v5, v5, v5
	v_fmac_f32_e32 v5, v4, v4
	v_mul_f32_e32 v4, v7, v7
	v_fmac_f32_e32 v4, v6, v6
	v_mul_f32_e32 v1, v1, v1
	v_add_f32_e32 v4, v5, v4
	v_fmac_f32_e32 v1, v0, v0
	v_add_f32_e32 v0, v4, v1
	v_mul_f32_e32 v1, v3, v3
	v_fmac_f32_e32 v1, v2, v2
	v_add_f32_e32 v0, v1, v0
	v_mov_b32_e32 v1, v0
	s_nop 1
	v_permlane16_swap_b32_e32 v1, v0
	v_add_f32_e32 v0, v0, v1
	v_mov_b32_e32 v1, v0
	s_nop 1
	v_permlane32_swap_b32_e32 v1, v0
	s_and_saveexec_b64 s[46:47], s[0:1]
	s_cbranch_execz .LBB0_791
	v_add_f32_e32 v0, v0, v1
	ds_write_b32 v15, v0 offset:5648

; #define FOR_AI_M _Pragma("unroll") for (int ai = 0; ai < 2; ++ai) _Pragma("unroll") for (int m = 0; m < 4; ++m)
; #define FOR_BJ _Pragma("unroll") for (int bj = 0; bj < 2; ++bj)
; __device__ __forceinline__ void head_ss(const f32x4 (&v)[2][2][4][2], float (&tot)[2][4][2], LAS float* X, int wr, int wc, int fr, int fq) {
;     ...
;                 const f32x4 a = v[ai][bj][m][0], b = v[ai][bj][m][1];
;                 float s = (a[0] * a[0] + a[1] * a[1]) + (a[2] * a[2] + a[3] * a[3]) + (b[0] * b[0] + b[1] * b[1]) + (b[2] * b[2] + b[3] * b[3]);
;                 s += __shfl_xor(s, 16); s += __shfl_xor(s, 32);
;                 if (fq == 0) X[((ai * 128 + wr * 64 + m * 16 + fr) * 2 + bj) * 4 + wc] = s;
;     __device__ __forceinline__ void operator()(f32x4 (&acc)[2][2][4][2], const Unit& u, int wr, int wc, int fr, int fq) const {
;         FOR_AI_M { const int grow = u.pm * BM + ai * HALF + wr * 64 + m * 16 + fr;
;             const f32x4 a0 = *(const f32x4*)(SS2 + (size_t)grow * 8), a1 = *(const f32x4*)(SS2 + (size_t)grow * 8 + 4);
;             const float r2 = rsqrtf(((a0[0] + a0[1]) + (a0[2] + a0[3]) + (a1[0] + a1[1]) + (a1[2] + a1[3])) * (1.f / 2048.f) + EPS);
;             FOR_BJ { acc[ai][bj][m][0] *= r2; acc[ai][bj][m][1] *= r2; } }
.LBB0_867:
	v_lshl_add_u32 v210, s4, 8, v179
	v_ashrrev_i32_e32 v211, 31, v210
	v_lshlrev_b64 v[128:129], 5, v[210:211]
	v_or_b32_e32 v208, 16, v210
	s_waitcnt vmcnt(0)
	v_lshl_add_u64 v[128:129], s[6:7], 0, v[128:129]
	v_ashrrev_i32_e32 v209, 31, v208
	global_load_dwordx4 v[212:215], v[128:129], off
	global_load_dwordx4 v[222:225], v[128:129], off offset:16
	v_lshlrev_b64 v[128:129], 5, v[208:209]
	v_lshl_add_u64 v[128:129], s[6:7], 0, v[128:129]
	global_load_dwordx4 v[226:229], v[128:129], off
	global_load_dwordx4 v[230:233], v[128:129], off offset:16
	v_or_b32_e32 v206, 32, v210
	v_or_b32_e32 v204, 48, v210
	v_add_u32_e32 v202, 0x80, v210
	v_add_u32_e32 v200, 0x90, v210
	v_add_u32_e32 v198, 0xa0, v210
	v_add_u32_e32 v196, 0xb0, v210
	v_ashrrev_i32_e32 v207, 31, v206
	v_ashrrev_i32_e32 v205, 31, v204
	v_ashrrev_i32_e32 v203, 31, v202
	v_ashrrev_i32_e32 v201, 31, v200
	v_ashrrev_i32_e32 v199, 31, v198
	v_ashrrev_i32_e32 v197, 31, v196
	v_lshlrev_b64 v[128:129], 5, v[206:207]
	v_lshlrev_b64 v[130:131], 5, v[204:205]
	v_lshlrev_b64 v[132:133], 5, v[202:203]
	v_lshlrev_b64 v[134:135], 5, v[200:201]
	v_lshlrev_b64 v[136:137], 5, v[198:199]
	v_lshlrev_b64 v[138:139], 5, v[196:197]
	v_lshl_add_u64 v[128:129], s[6:7], 0, v[128:129]
	v_lshl_add_u64 v[130:131], s[6:7], 0, v[130:131]
	v_lshl_add_u64 v[132:133], s[6:7], 0, v[132:133]
	v_lshl_add_u64 v[134:135], s[6:7], 0, v[134:135]
	v_lshl_add_u64 v[140:141], s[6:7], 0, v[136:137]
	v_lshl_add_u64 v[234:235], s[6:7], 0, v[138:139]
	global_load_dwordx4 v[168:171], v[128:129], off offset:16
	global_load_dwordx4 v[172:175], v[128:129], off
	global_load_dwordx4 v[160:163], v[130:131], off offset:16
	global_load_dwordx4 v[164:167], v[130:131], off
	global_load_dwordx4 v[152:155], v[132:133], off offset:16
	global_load_dwordx4 v[156:159], v[132:133], off
	global_load_dwordx4 v[144:147], v[134:135], off offset:16
	global_load_dwordx4 v[148:151], v[134:135], off
	global_load_dwordx4 v[136:139], v[140:141], off offset:16
	s_nop 0
	global_load_dwordx4 v[140:143], v[140:141], off
	s_nop 0
	global_load_dwordx4 v[128:131], v[234:235], off offset:16
	global_load_dwordx4 v[132:135], v[234:235], off
	v_and_b32_e32 v234, 64, v221
	v_add_u32_e32 v237, 64, v234
	v_xor_b32_e32 v236, 16, v221
	v_cmp_lt_i32_e64 s[4:5], v236, v237
	s_waitcnt vmcnt(0)
	v_mov_b32_e32 v234, v213
	v_mov_b32_e32 v235, v214
	v_mov_b32_e32 v213, v215
	v_mov_b32_e32 v214, v224
	v_mov_b32_e32 v215, v222
	v_mov_b32_e32 v222, v225
	v_pk_add_f32 v[214:215], v[214:215], v[222:223]
	v_mov_b32_e32 v222, v227
	v_mov_b32_e32 v223, v228
	v_mov_b32_e32 v227, v229
	v_pk_add_f32 v[212:213], v[234:235], v[212:213]
	v_mov_b32_e32 v224, v232
	v_mov_b32_e32 v225, v230
	v_mov_b32_e32 v230, v233
	v_pk_add_f32 v[222:223], v[222:223], v[226:227]
	v_pk_add_f32 v[224:225], v[224:225], v[230:231]
	v_mov_b32_e32 v227, v212
	v_mov_b32_e32 v226, v222
	v_mov_b32_e32 v212, v223
	v_mov_b32_e32 v229, v215
	v_mov_b32_e32 v228, v225
	v_pk_add_f32 v[212:213], v[226:227], v[212:213]
	v_mov_b32_e32 v225, v214
	v_pk_add_f32 v[212:213], v[212:213], v[228:229]
	s_nop 0
	v_pk_add_f32 v[212:213], v[224:225], v[212:213]
	s_nop 0
	v_pk_fma_f32 v[212:213], v[212:213], s[20:21], v[194:195] op_sel_hi:[1,0,0]
	s_nop 0
	v_mul_f32_e32 v214, 0x4b800000, v213
	v_cmp_gt_f32_e32 vcc, s67, v213
	s_nop 1
	v_cndmask_b32_e32 v213, v213, v214, vcc
	v_rsq_f32_e32 v213, v213
	v_cndmask_b32_e64 v214, v221, v236, s[4:5]
	v_lshlrev_b32_e32 v222, 2, v214
	v_mul_f32_e32 v214, 0x45800000, v213
	v_cndmask_b32_e32 v214, v213, v214, vcc
	v_pk_mul_f32 v[126:127], v[126:127], v[214:215] op_sel_hi:[1,0]
	v_pk_mul_f32 v[124:125], v[124:125], v[214:215] op_sel_hi:[1,0]
	v_pk_mul_f32 v[122:123], v[122:123], v[214:215] op_sel_hi:[1,0]
	v_pk_mul_f32 v[120:121], v[120:121], v[214:215] op_sel_hi:[1,0]
	v_mul_f32_e32 v213, v125, v125
	v_mul_f32_e32 v215, v127, v127
	v_mul_f32_e32 v223, v121, v121
	v_fmac_f32_e32 v213, v124, v124
	v_fmac_f32_e32 v215, v126, v126
	v_mul_f32_e32 v224, v123, v123
	v_fmac_f32_e32 v223, v120, v120
	v_add_f32_e32 v213, v213, v215
	v_add_f32_e32 v213, v223, v213
	v_fmac_f32_e32 v224, v122, v122
	v_add_f32_e32 v213, v224, v213
	v_mov_b32_e32 v215, v213
	s_nop 1
	v_permlane16_swap_b32_e32 v215, v213
	v_xor_b32_e32 v223, 32, v221
	v_cmp_lt_i32_e32 vcc, v223, v237
	v_add_f32_e32 v213, v213, v215
	v_cndmask_b32_e32 v223, v221, v223, vcc
	v_lshlrev_b32_e32 v224, 2, v223
	v_mov_b32_e32 v215, v213
	s_nop 1
	v_permlane32_swap_b32_e32 v215, v213
	v_cmp_gt_f32_e32 vcc, s67, v212
	v_add_u32_e32 v223, s79, v216
	s_and_saveexec_b64 s[4:5], s[0:1]
	s_cbranch_execz .LBB0_869
	v_add_f32_e32 v213, v213, v215
	ds_write_b32 v223, v213
.LBB0_869:
	s_or_b64 exec, exec, s[4:5]
	v_mov_b32_e32 v215, v214
	v_mov_b32_e32 v226, v214
	v_mov_b32_e32 v227, v214
	v_pk_mul_f32 v[118:119], v[118:119], v[226:227]
	v_pk_mul_f32 v[116:117], v[116:117], v[214:215]
	v_pk_mul_f32 v[112:113], v[112:113], v[214:215]
	v_mul_f32_e32 v213, v117, v117
	v_mul_f32_e32 v214, v119, v119
	v_fmac_f32_e32 v213, v116, v116
	v_fmac_f32_e32 v214, v118, v118
	v_add_f32_e32 v213, v213, v214
	v_mul_f32_e32 v214, v113, v113
	v_pk_mul_f32 v[114:115], v[114:115], v[226:227]
	v_fmac_f32_e32 v214, v112, v112
	v_add_f32_e32 v213, v214, v213
	v_mul_f32_e32 v214, v115, v115
	v_fmac_f32_e32 v214, v114, v114
	v_add_f32_e32 v213, v214, v213
	v_mov_b32_e32 v214, v213
	s_nop 1
	v_permlane16_swap_b32_e32 v214, v213
	v_add_f32_e32 v213, v213, v214
	v_mov_b32_e32 v214, v213
	s_nop 1
	v_permlane32_swap_b32_e32 v214, v213
	s_and_saveexec_b64 s[4:5], s[0:1]
	s_cbranch_execz .LBB0_871
	v_add_f32_e32 v213, v213, v214
	ds_write_b32 v223, v213 offset:16
; #define FOR_AI_M _Pragma("unroll") for (int ai = 0; ai < 2; ++ai) _Pragma("unroll") for (int m = 0; m < 4; ++m)
; #define FOR_BJ _Pragma("unroll") for (int bj = 0; bj < 2; ++bj)
; __device__ __forceinline__ void head_ss(const f32x4 (&v)[2][2][4][2], float (&tot)[2][4][2], LAS float* X, int wr, int wc, int fr, int fq) {
;     ...
;                 const f32x4 a = v[ai][bj][m][0], b = v[ai][bj][m][1];
;                 float s = (a[0] * a[0] + a[1] * a[1]) + (a[2] * a[2] + a[3] * a[3]) + (b[0] * b[0] + b[1] * b[1]) + (b[2] * b[2] + b[3] * b[3]);
;                 s += __shfl_xor(s, 16); s += __shfl_xor(s, 32);
;                 if (fq == 0) X[((ai * 128 + wr * 64 + m * 16 + fr) * 2 + bj) * 4 + wc] = s;
;     __device__ __forceinline__ void operator()(f32x4 (&acc)[2][2][4][2], const Unit& u, int wr, int wc, int fr, int fq) const {
;         FOR_AI_M { const int grow = u.pm * BM + ai * HALF + wr * 64 + m * 16 + fr;
;             const f32x4 a0 = *(const f32x4*)(SS2 + (size_t)grow * 8), a1 = *(const f32x4*)(SS2 + (size_t)grow * 8 + 4);
;             const float r2 = rsqrtf(((a0[0] + a0[1]) + (a0[2] + a0[3]) + (a1[0] + a1[1]) + (a1[2] + a1[3])) * (1.f / 2048.f) + EPS);
;             FOR_BJ { acc[ai][bj][m][0] *= r2; acc[ai][bj][m][1] *= r2; } }
.LBB0_871:
	s_or_b64 exec, exec, s[4:5]
	v_mul_f32_e32 v213, 0x4b800000, v212
	v_cndmask_b32_e32 v212, v212, v213, vcc
	v_rsq_f32_e32 v212, v212
	s_nop 0
	v_mul_f32_e32 v213, 0x45800000, v212
	v_cndmask_b32_e32 v212, v212, v213, vcc
	v_pk_mul_f32 v[110:111], v[110:111], v[212:213] op_sel_hi:[1,0]
	v_pk_mul_f32 v[108:109], v[108:109], v[212:213] op_sel_hi:[1,0]
	v_pk_mul_f32 v[106:107], v[106:107], v[212:213] op_sel_hi:[1,0]
	v_pk_mul_f32 v[104:105], v[104:105], v[212:213] op_sel_hi:[1,0]
	v_mul_f32_e32 v213, v109, v109
	v_mul_f32_e32 v214, v111, v111
	v_fmac_f32_e32 v213, v108, v108
	v_fmac_f32_e32 v214, v110, v110
	v_add_f32_e32 v213, v213, v214
	v_mul_f32_e32 v214, v105, v105
	v_fmac_f32_e32 v214, v104, v104
	v_add_f32_e32 v213, v214, v213
	v_mul_f32_e32 v214, v107, v107
	v_fmac_f32_e32 v214, v106, v106
	v_add_f32_e32 v213, v214, v213
	v_mov_b32_e32 v214, v213
	s_nop 1
	v_permlane16_swap_b32_e32 v214, v213
	v_add_f32_e32 v213, v213, v214
	v_mov_b32_e32 v214, v213
	s_nop 1
	v_permlane32_swap_b32_e32 v214, v213
	s_and_saveexec_b64 s[4:5], s[0:1]
	s_cbranch_execz .LBB0_873
	v_add_f32_e32 v213, v213, v214
	ds_write_b32 v223, v213 offset:512
.LBB0_873:
	s_or_b64 exec, exec, s[4:5]
	v_mov_b32_e32 v213, v212
	v_mov_b32_e32 v214, v212
	v_mov_b32_e32 v215, v212
	v_pk_mul_f32 v[102:103], v[102:103], v[214:215]
	v_pk_mul_f32 v[100:101], v[100:101], v[212:213]
	v_pk_mul_f32 v[96:97], v[96:97], v[212:213]
	v_mul_f32_e32 v212, v101, v101
	v_mul_f32_e32 v213, v103, v103
	v_fmac_f32_e32 v212, v100, v100
	v_fmac_f32_e32 v213, v102, v102
	v_add_f32_e32 v212, v212, v213
	v_mul_f32_e32 v213, v97, v97
	v_pk_mul_f32 v[98:99], v[98:99], v[214:215]
	v_fmac_f32_e32 v213, v96, v96
	v_add_f32_e32 v212, v213, v212
	v_mul_f32_e32 v213, v99, v99
	v_fmac_f32_e32 v213, v98, v98
	v_add_f32_e32 v212, v213, v212
	v_mov_b32_e32 v213, v212
	s_nop 1
	v_permlane16_swap_b32_e32 v213, v212
	v_add_f32_e32 v212, v212, v213
	v_mov_b32_e32 v213, v212
	s_nop 1
	v_permlane32_swap_b32_e32 v213, v212
	s_and_saveexec_b64 s[4:5], s[0:1]
	s_cbranch_execz .LBB0_875
	v_add_f32_e32 v212, v212, v213
	ds_write_b32 v223, v212 offset:528
.LBB0_875:
	s_or_b64 exec, exec, s[4:5]
	v_mov_b32_e32 v212, v173
	v_mov_b32_e32 v213, v174
	v_mov_b32_e32 v173, v175
	v_mov_b32_e32 v174, v170
	v_mov_b32_e32 v175, v168
	v_mov_b32_e32 v168, v171
	v_mov_b32_e32 v170, v165
	v_mov_b32_e32 v171, v166
	v_mov_b32_e32 v165, v167
	v_pk_add_f32 v[172:173], v[212:213], v[172:173]
	v_pk_add_f32 v[164:165], v[170:171], v[164:165]
	v_mov_b32_e32 v166, v162
	v_mov_b32_e32 v167, v160
	v_mov_b32_e32 v160, v163
	v_pk_add_f32 v[168:169], v[174:175], v[168:169]
	v_pk_add_f32 v[160:161], v[166:167], v[160:161]
	v_mov_b32_e32 v162, v164
	v_mov_b32_e32 v163, v172
	v_mov_b32_e32 v172, v165
	v_pk_add_f32 v[162:163], v[162:163], v[172:173]
	v_mov_b32_e32 v164, v161
	v_mov_b32_e32 v165, v169
	v_pk_add_f32 v[162:163], v[162:163], v[164:165]
	v_mov_b32_e32 v161, v168
	v_pk_add_f32 v[160:161], v[160:161], v[162:163]
	s_nop 0
	v_pk_fma_f32 v[160:161], v[160:161], s[20:21], v[194:195] op_sel_hi:[1,0,0]
	s_nop 0
	v_mul_f32_e32 v162, 0x4b800000, v161
	v_cmp_gt_f32_e32 vcc, s67, v161
	s_nop 1
	v_cndmask_b32_e32 v161, v161, v162, vcc
	v_rsq_f32_e32 v161, v161
	s_nop 0
	v_mul_f32_e32 v162, 0x45800000, v161
	v_cndmask_b32_e32 v162, v161, v162, vcc
	v_pk_mul_f32 v[94:95], v[94:95], v[162:163] op_sel_hi:[1,0]
	v_pk_mul_f32 v[92:93], v[92:93], v[162:163] op_sel_hi:[1,0]
	v_pk_mul_f32 v[90:91], v[90:91], v[162:163] op_sel_hi:[1,0]
	v_pk_mul_f32 v[88:89], v[88:89], v[162:163] op_sel_hi:[1,0]
	v_mul_f32_e32 v161, v93, v93
	v_mul_f32_e32 v163, v95, v95
	v_fmac_f32_e32 v161, v92, v92
	v_fmac_f32_e32 v163, v94, v94
	v_add_f32_e32 v161, v161, v163
	v_mul_f32_e32 v163, v89, v89
	v_fmac_f32_e32 v163, v88, v88
	v_add_f32_e32 v161, v163, v161
	v_mul_f32_e32 v163, v91, v91
	v_fmac_f32_e32 v163, v90, v90
	v_add_f32_e32 v161, v163, v161
	v_mov_b32_e32 v163, v161
	s_nop 1
	v_permlane16_swap_b32_e32 v163, v161
	v_cmp_gt_f32_e32 vcc, s67, v160
	v_add_f32_e32 v161, v161, v163
	v_mov_b32_e32 v163, v161
	s_nop 1
	v_permlane32_swap_b32_e32 v163, v161
	s_and_saveexec_b64 s[4:5], s[0:1]
	s_cbranch_execz .LBB0_877
	v_add_f32_e32 v161, v161, v163
	ds_write_b32 v223, v161 offset:1024
.LBB0_877:
	s_or_b64 exec, exec, s[4:5]
	v_mov_b32_e32 v163, v162
	v_mov_b32_e32 v164, v162
	v_mov_b32_e32 v165, v162
	v_pk_mul_f32 v[86:87], v[86:87], v[164:165]
	v_pk_mul_f32 v[84:85], v[84:85], v[162:163]
	v_pk_mul_f32 v[80:81], v[80:81], v[162:163]
	v_mul_f32_e32 v161, v85, v85
	v_mul_f32_e32 v162, v87, v87
	v_fmac_f32_e32 v161, v84, v84
	v_fmac_f32_e32 v162, v86, v86
	v_add_f32_e32 v161, v161, v162
	v_mul_f32_e32 v162, v81, v81
	v_pk_mul_f32 v[82:83], v[82:83], v[164:165]
	v_fmac_f32_e32 v162, v80, v80
	v_add_f32_e32 v161, v162, v161
	v_mul_f32_e32 v162, v83, v83
	v_fmac_f32_e32 v162, v82, v82
	v_add_f32_e32 v161, v162, v161
	v_mov_b32_e32 v162, v161
	s_nop 1
	v_permlane16_swap_b32_e32 v162, v161
	v_add_f32_e32 v161, v161, v162
	v_mov_b32_e32 v162, v161
	s_nop 1
	v_permlane32_swap_b32_e32 v162, v161
	s_and_saveexec_b64 s[4:5], s[0:1]
	s_cbranch_execz .LBB0_879
	v_add_f32_e32 v161, v161, v162
	ds_write_b32 v223, v161 offset:1040
; #define FOR_AI_M _Pragma("unroll") for (int ai = 0; ai < 2; ++ai) _Pragma("unroll") for (int m = 0; m < 4; ++m)
; #define FOR_BJ _Pragma("unroll") for (int bj = 0; bj < 2; ++bj)
; __device__ __forceinline__ void head_ss(const f32x4 (&v)[2][2][4][2], float (&tot)[2][4][2], LAS float* X, int wr, int wc, int fr, int fq) {
;     ...
;                 const f32x4 a = v[ai][bj][m][0], b = v[ai][bj][m][1];
;                 float s = (a[0] * a[0] + a[1] * a[1]) + (a[2] * a[2] + a[3] * a[3]) + (b[0] * b[0] + b[1] * b[1]) + (b[2] * b[2] + b[3] * b[3]);
;                 s += __shfl_xor(s, 16); s += __shfl_xor(s, 32);
;                 if (fq == 0) X[((ai * 128 + wr * 64 + m * 16 + fr) * 2 + bj) * 4 + wc] = s;
;     __device__ __forceinline__ void operator()(f32x4 (&acc)[2][2][4][2], const Unit& u, int wr, int wc, int fr, int fq) const {
;         FOR_AI_M { const int grow = u.pm * BM + ai * HALF + wr * 64 + m * 16 + fr;
;             const f32x4 a0 = *(const f32x4*)(SS2 + (size_t)grow * 8), a1 = *(const f32x4*)(SS2 + (size_t)grow * 8 + 4);
;             const float r2 = rsqrtf(((a0[0] + a0[1]) + (a0[2] + a0[3]) + (a1[0] + a1[1]) + (a1[2] + a1[3])) * (1.f / 2048.f) + EPS);
;             FOR_BJ { acc[ai][bj][m][0] *= r2; acc[ai][bj][m][1] *= r2; } }
.LBB0_879:
	s_or_b64 exec, exec, s[4:5]
	v_mul_f32_e32 v161, 0x4b800000, v160
	v_cndmask_b32_e32 v160, v160, v161, vcc
	v_rsq_f32_e32 v160, v160
	s_nop 0
	v_mul_f32_e32 v161, 0x45800000, v160
	v_cndmask_b32_e32 v160, v160, v161, vcc
	v_pk_mul_f32 v[78:79], v[78:79], v[160:161] op_sel_hi:[1,0]
	v_pk_mul_f32 v[76:77], v[76:77], v[160:161] op_sel_hi:[1,0]
	v_pk_mul_f32 v[74:75], v[74:75], v[160:161] op_sel_hi:[1,0]
	v_pk_mul_f32 v[72:73], v[72:73], v[160:161] op_sel_hi:[1,0]
	v_mul_f32_e32 v161, v77, v77
	v_mul_f32_e32 v162, v79, v79
	v_fmac_f32_e32 v161, v76, v76
	v_fmac_f32_e32 v162, v78, v78
	v_add_f32_e32 v161, v161, v162
	v_mul_f32_e32 v162, v73, v73
	v_fmac_f32_e32 v162, v72, v72
	v_add_f32_e32 v161, v162, v161
	v_mul_f32_e32 v162, v75, v75
	v_fmac_f32_e32 v162, v74, v74
	v_add_f32_e32 v161, v162, v161
	v_mov_b32_e32 v162, v161
	s_nop 1
	v_permlane16_swap_b32_e32 v162, v161
	v_add_f32_e32 v161, v161, v162
	v_mov_b32_e32 v162, v161
	s_nop 1
	v_permlane32_swap_b32_e32 v162, v161
	s_and_saveexec_b64 s[4:5], s[0:1]
	s_cbranch_execz .LBB0_881
	v_add_f32_e32 v161, v161, v162
	ds_write_b32 v223, v161 offset:1536
.LBB0_881:
	s_or_b64 exec, exec, s[4:5]
	v_mov_b32_e32 v161, v160
	v_mov_b32_e32 v162, v160
	v_mov_b32_e32 v163, v160
	v_pk_mul_f32 v[70:71], v[70:71], v[162:163]
	v_pk_mul_f32 v[68:69], v[68:69], v[160:161]
	v_pk_mul_f32 v[64:65], v[64:65], v[160:161]
	v_mul_f32_e32 v160, v69, v69
	v_mul_f32_e32 v161, v71, v71
	v_fmac_f32_e32 v160, v68, v68
	v_fmac_f32_e32 v161, v70, v70
	v_add_f32_e32 v160, v160, v161
	v_mul_f32_e32 v161, v65, v65
	v_pk_mul_f32 v[66:67], v[66:67], v[162:163]
	v_fmac_f32_e32 v161, v64, v64
	v_add_f32_e32 v160, v161, v160
	v_mul_f32_e32 v161, v67, v67
	v_fmac_f32_e32 v161, v66, v66
	v_add_f32_e32 v160, v161, v160
	v_mov_b32_e32 v161, v160
	s_nop 1
	v_permlane16_swap_b32_e32 v161, v160
	v_add_f32_e32 v160, v160, v161
	v_mov_b32_e32 v161, v160
	s_nop 1
	v_permlane32_swap_b32_e32 v161, v160
	s_and_saveexec_b64 s[4:5], s[0:1]
	s_cbranch_execz .LBB0_883
	v_add_f32_e32 v160, v160, v161
	ds_write_b32 v223, v160 offset:1552
.LBB0_883:
	s_or_b64 exec, exec, s[4:5]
	v_mov_b32_e32 v160, v157
	v_mov_b32_e32 v161, v158
	v_mov_b32_e32 v157, v159
	v_mov_b32_e32 v158, v154
	v_mov_b32_e32 v159, v152
	v_mov_b32_e32 v152, v155
	v_mov_b32_e32 v154, v149
	v_mov_b32_e32 v155, v150
	v_mov_b32_e32 v149, v151
	v_pk_add_f32 v[156:157], v[160:161], v[156:157]
	v_pk_add_f32 v[148:149], v[154:155], v[148:149]
	v_mov_b32_e32 v150, v146
	v_mov_b32_e32 v151, v144
	v_mov_b32_e32 v144, v147
	v_pk_add_f32 v[152:153], v[158:159], v[152:153]
	v_pk_add_f32 v[144:145], v[150:151], v[144:145]
	v_mov_b32_e32 v146, v148
	v_mov_b32_e32 v147, v156
	v_mov_b32_e32 v156, v149
	v_pk_add_f32 v[146:147], v[146:147], v[156:157]
	v_mov_b32_e32 v148, v145
	v_mov_b32_e32 v149, v153
	v_pk_add_f32 v[146:147], v[146:147], v[148:149]
	v_mov_b32_e32 v145, v152
	v_pk_add_f32 v[144:145], v[144:145], v[146:147]
	s_nop 0
	v_pk_fma_f32 v[144:145], v[144:145], s[20:21], v[194:195] op_sel_hi:[1,0,0]
	s_nop 0
	v_mul_f32_e32 v146, 0x4b800000, v145
	v_cmp_gt_f32_e32 vcc, s67, v145
	s_nop 1
	v_cndmask_b32_e32 v145, v145, v146, vcc
	v_rsq_f32_e32 v145, v145
	s_nop 0
	v_mul_f32_e32 v146, 0x45800000, v145
	v_cndmask_b32_e32 v146, v145, v146, vcc
	v_pk_mul_f32 v[62:63], v[62:63], v[146:147] op_sel_hi:[1,0]
	v_pk_mul_f32 v[60:61], v[60:61], v[146:147] op_sel_hi:[1,0]
	v_pk_mul_f32 v[58:59], v[58:59], v[146:147] op_sel_hi:[1,0]
	v_pk_mul_f32 v[56:57], v[56:57], v[146:147] op_sel_hi:[1,0]
	v_mul_f32_e32 v145, v61, v61
	v_mul_f32_e32 v147, v63, v63
	v_fmac_f32_e32 v145, v60, v60
	v_fmac_f32_e32 v147, v62, v62
	v_add_f32_e32 v145, v145, v147
	v_mul_f32_e32 v147, v57, v57
	v_fmac_f32_e32 v147, v56, v56
	v_add_f32_e32 v145, v147, v145
	v_mul_f32_e32 v147, v59, v59
	v_fmac_f32_e32 v147, v58, v58
	v_add_f32_e32 v145, v147, v145
	v_mov_b32_e32 v147, v145
	s_nop 1
	v_permlane16_swap_b32_e32 v147, v145
	v_cmp_gt_f32_e32 vcc, s67, v144
	v_add_f32_e32 v145, v145, v147
	v_mov_b32_e32 v147, v145
	s_nop 1
	v_permlane32_swap_b32_e32 v147, v145
	s_and_saveexec_b64 s[4:5], s[0:1]
	s_cbranch_execz .LBB0_885
	v_add_f32_e32 v145, v145, v147
	ds_write_b32 v223, v145 offset:4096
.LBB0_885:
	s_or_b64 exec, exec, s[4:5]
	v_mov_b32_e32 v147, v146
	v_mov_b32_e32 v148, v146
	v_mov_b32_e32 v149, v146
	v_pk_mul_f32 v[54:55], v[54:55], v[148:149]
	v_pk_mul_f32 v[52:53], v[52:53], v[146:147]
	v_pk_mul_f32 v[48:49], v[48:49], v[146:147]
	v_mul_f32_e32 v145, v53, v53
	v_mul_f32_e32 v146, v55, v55
	v_fmac_f32_e32 v145, v52, v52
	v_fmac_f32_e32 v146, v54, v54
	v_add_f32_e32 v145, v145, v146
	v_mul_f32_e32 v146, v49, v49
	v_pk_mul_f32 v[50:51], v[50:51], v[148:149]
	v_fmac_f32_e32 v146, v48, v48
	v_add_f32_e32 v145, v146, v145
	v_mul_f32_e32 v146, v51, v51
	v_fmac_f32_e32 v146, v50, v50
	v_add_f32_e32 v145, v146, v145
	v_mov_b32_e32 v146, v145
	s_nop 1
	v_permlane16_swap_b32_e32 v146, v145
	v_add_f32_e32 v145, v145, v146
	v_mov_b32_e32 v146, v145
	s_nop 1
	v_permlane32_swap_b32_e32 v146, v145
	s_and_saveexec_b64 s[4:5], s[0:1]
	s_cbranch_execz .LBB0_887
	v_add_f32_e32 v145, v145, v146
	ds_write_b32 v223, v145 offset:4112
; #define FOR_AI_M _Pragma("unroll") for (int ai = 0; ai < 2; ++ai) _Pragma("unroll") for (int m = 0; m < 4; ++m)
; #define FOR_BJ _Pragma("unroll") for (int bj = 0; bj < 2; ++bj)
; __device__ __forceinline__ void head_ss(const f32x4 (&v)[2][2][4][2], float (&tot)[2][4][2], LAS float* X, int wr, int wc, int fr, int fq) {
;     ...
;                 const f32x4 a = v[ai][bj][m][0], b = v[ai][bj][m][1];
;                 float s = (a[0] * a[0] + a[1] * a[1]) + (a[2] * a[2] + a[3] * a[3]) + (b[0] * b[0] + b[1] * b[1]) + (b[2] * b[2] + b[3] * b[3]);
;                 s += __shfl_xor(s, 16); s += __shfl_xor(s, 32);
;                 if (fq == 0) X[((ai * 128 + wr * 64 + m * 16 + fr) * 2 + bj) * 4 + wc] = s;
;     __device__ __forceinline__ void operator()(f32x4 (&acc)[2][2][4][2], const Unit& u, int wr, int wc, int fr, int fq) const {
;         FOR_AI_M { const int grow = u.pm * BM + ai * HALF + wr * 64 + m * 16 + fr;
;             const f32x4 a0 = *(const f32x4*)(SS2 + (size_t)grow * 8), a1 = *(const f32x4*)(SS2 + (size_t)grow * 8 + 4);
;             const float r2 = rsqrtf(((a0[0] + a0[1]) + (a0[2] + a0[3]) + (a1[0] + a1[1]) + (a1[2] + a1[3])) * (1.f / 2048.f) + EPS);
;             FOR_BJ { acc[ai][bj][m][0] *= r2; acc[ai][bj][m][1] *= r2; } }
.LBB0_887:
	s_or_b64 exec, exec, s[4:5]
	v_mul_f32_e32 v145, 0x4b800000, v144
	v_cndmask_b32_e32 v144, v144, v145, vcc
	v_rsq_f32_e32 v144, v144
	s_nop 0
	v_mul_f32_e32 v145, 0x45800000, v144
	v_cndmask_b32_e32 v144, v144, v145, vcc
	v_pk_mul_f32 v[46:47], v[46:47], v[144:145] op_sel_hi:[1,0]
	v_pk_mul_f32 v[44:45], v[44:45], v[144:145] op_sel_hi:[1,0]
	v_pk_mul_f32 v[42:43], v[42:43], v[144:145] op_sel_hi:[1,0]
	v_pk_mul_f32 v[40:41], v[40:41], v[144:145] op_sel_hi:[1,0]
	v_mul_f32_e32 v145, v45, v45
	v_mul_f32_e32 v146, v47, v47
	v_fmac_f32_e32 v145, v44, v44
	v_fmac_f32_e32 v146, v46, v46
	v_add_f32_e32 v145, v145, v146
	v_mul_f32_e32 v146, v41, v41
	v_fmac_f32_e32 v146, v40, v40
	v_add_f32_e32 v145, v146, v145
	v_mul_f32_e32 v146, v43, v43
	v_fmac_f32_e32 v146, v42, v42
	v_add_f32_e32 v145, v146, v145
	v_mov_b32_e32 v146, v145
	s_nop 1
	v_permlane16_swap_b32_e32 v146, v145
	v_add_f32_e32 v145, v145, v146
	v_mov_b32_e32 v146, v145
	s_nop 1
	v_permlane32_swap_b32_e32 v146, v145
	s_and_saveexec_b64 s[4:5], s[0:1]
	s_cbranch_execz .LBB0_889
	v_add_f32_e32 v145, v145, v146
	ds_write_b32 v223, v145 offset:4608
.LBB0_889:
	s_or_b64 exec, exec, s[4:5]
	v_mov_b32_e32 v145, v144
	v_mov_b32_e32 v146, v144
	v_mov_b32_e32 v147, v144
	v_pk_mul_f32 v[38:39], v[38:39], v[146:147]
	v_pk_mul_f32 v[36:37], v[36:37], v[144:145]
	v_pk_mul_f32 v[32:33], v[32:33], v[144:145]
	v_mul_f32_e32 v144, v37, v37
	v_mul_f32_e32 v145, v39, v39
	v_fmac_f32_e32 v144, v36, v36
	v_fmac_f32_e32 v145, v38, v38
	v_add_f32_e32 v144, v144, v145
	v_mul_f32_e32 v145, v33, v33
	v_pk_mul_f32 v[34:35], v[34:35], v[146:147]
	v_fmac_f32_e32 v145, v32, v32
	v_add_f32_e32 v144, v145, v144
	v_mul_f32_e32 v145, v35, v35
	v_fmac_f32_e32 v145, v34, v34
	v_add_f32_e32 v144, v145, v144
	v_mov_b32_e32 v145, v144
	s_nop 1
	v_permlane16_swap_b32_e32 v145, v144
	v_add_f32_e32 v144, v144, v145
	v_mov_b32_e32 v145, v144
	s_nop 1
	v_permlane32_swap_b32_e32 v145, v144
	s_and_saveexec_b64 s[4:5], s[0:1]
	s_cbranch_execz .LBB0_891
	v_add_f32_e32 v144, v144, v145
	ds_write_b32 v223, v144 offset:4624
.LBB0_891:
	s_or_b64 exec, exec, s[4:5]
	v_mov_b32_e32 v144, v141
	v_mov_b32_e32 v145, v142
	v_mov_b32_e32 v141, v143
	v_mov_b32_e32 v142, v138
	v_mov_b32_e32 v143, v136
	v_mov_b32_e32 v136, v139
	v_mov_b32_e32 v138, v133
	v_mov_b32_e32 v139, v134
	v_mov_b32_e32 v133, v135
	v_pk_add_f32 v[140:141], v[144:145], v[140:141]
	v_pk_add_f32 v[132:133], v[138:139], v[132:133]
	v_mov_b32_e32 v134, v130
	v_mov_b32_e32 v135, v128
	v_mov_b32_e32 v128, v131
	v_pk_add_f32 v[136:137], v[142:143], v[136:137]
	v_pk_add_f32 v[128:129], v[134:135], v[128:129]
	v_mov_b32_e32 v130, v132
	v_mov_b32_e32 v131, v140
	v_mov_b32_e32 v140, v133
	v_pk_add_f32 v[130:131], v[130:131], v[140:141]
	v_mov_b32_e32 v132, v129
	v_mov_b32_e32 v133, v137
	v_pk_add_f32 v[130:131], v[130:131], v[132:133]
	v_mov_b32_e32 v129, v136
	v_pk_add_f32 v[128:129], v[128:129], v[130:131]
	s_nop 0
	v_pk_fma_f32 v[128:129], v[128:129], s[20:21], v[194:195] op_sel_hi:[1,0,0]
	s_nop 0
	v_mul_f32_e32 v130, 0x4b800000, v129
	v_cmp_gt_f32_e32 vcc, s67, v129
	s_nop 1
	v_cndmask_b32_e32 v129, v129, v130, vcc
	v_rsq_f32_e32 v129, v129
	s_nop 0
	v_mul_f32_e32 v130, 0x45800000, v129
	v_cndmask_b32_e32 v130, v129, v130, vcc
	v_pk_mul_f32 v[30:31], v[30:31], v[130:131] op_sel_hi:[1,0]
	v_pk_mul_f32 v[28:29], v[28:29], v[130:131] op_sel_hi:[1,0]
	v_pk_mul_f32 v[26:27], v[26:27], v[130:131] op_sel_hi:[1,0]
	v_pk_mul_f32 v[24:25], v[24:25], v[130:131] op_sel_hi:[1,0]
	v_mul_f32_e32 v129, v29, v29
	v_mul_f32_e32 v131, v31, v31
	v_fmac_f32_e32 v129, v28, v28
	v_fmac_f32_e32 v131, v30, v30
	v_add_f32_e32 v129, v129, v131
	v_mul_f32_e32 v131, v25, v25
	v_fmac_f32_e32 v131, v24, v24
	v_add_f32_e32 v129, v131, v129
	v_mul_f32_e32 v131, v27, v27
	v_fmac_f32_e32 v131, v26, v26
	v_add_f32_e32 v129, v131, v129
	v_mov_b32_e32 v131, v129
	s_nop 1
	v_permlane16_swap_b32_e32 v131, v129
	v_cmp_gt_f32_e32 vcc, s67, v128
	v_add_f32_e32 v129, v129, v131
	v_mov_b32_e32 v131, v129
	s_nop 1
	v_permlane32_swap_b32_e32 v131, v129
	s_and_saveexec_b64 s[4:5], s[0:1]
	s_cbranch_execz .LBB0_893
	v_add_f32_e32 v129, v129, v131
	ds_write_b32 v223, v129 offset:5120
; #define FOR_AI_M _Pragma("unroll") for (int ai = 0; ai < 2; ++ai) _Pragma("unroll") for (int m = 0; m < 4; ++m)
; #define FOR_BJ _Pragma("unroll") for (int bj = 0; bj < 2; ++bj)
; __device__ __forceinline__ void head_ss(const f32x4 (&v)[2][2][4][2], float (&tot)[2][4][2], LAS float* X, int wr, int wc, int fr, int fq) {
;     ...
;                 const f32x4 a = v[ai][bj][m][0], b = v[ai][bj][m][1];
;                 float s = (a[0] * a[0] + a[1] * a[1]) + (a[2] * a[2] + a[3] * a[3]) + (b[0] * b[0] + b[1] * b[1]) + (b[2] * b[2] + b[3] * b[3]);
;                 s += __shfl_xor(s, 16); s += __shfl_xor(s, 32);
;                 if (fq == 0) X[((ai * 128 + wr * 64 + m * 16 + fr) * 2 + bj) * 4 + wc] = s;
;     __device__ __forceinline__ void operator()(f32x4 (&acc)[2][2][4][2], const Unit& u, int wr, int wc, int fr, int fq) const {
;         FOR_AI_M { const int grow = u.pm * BM + ai * HALF + wr * 64 + m * 16 + fr;
;             const f32x4 a0 = *(const f32x4*)(SS2 + (size_t)grow * 8), a1 = *(const f32x4*)(SS2 + (size_t)grow * 8 + 4);
;             const float r2 = rsqrtf(((a0[0] + a0[1]) + (a0[2] + a0[3]) + (a1[0] + a1[1]) + (a1[2] + a1[3])) * (1.f / 2048.f) + EPS);
;             FOR_BJ { acc[ai][bj][m][0] *= r2; acc[ai][bj][m][1] *= r2; } }
.LBB0_893:
	s_or_b64 exec, exec, s[4:5]
	v_mov_b32_e32 v131, v130
	v_mov_b32_e32 v132, v130
	v_mov_b32_e32 v133, v130
	v_pk_mul_f32 v[22:23], v[22:23], v[132:133]
	v_pk_mul_f32 v[20:21], v[20:21], v[130:131]
	v_pk_mul_f32 v[16:17], v[16:17], v[130:131]
	v_mul_f32_e32 v129, v21, v21
	v_mul_f32_e32 v130, v23, v23
	v_fmac_f32_e32 v129, v20, v20
	v_fmac_f32_e32 v130, v22, v22
	v_add_f32_e32 v129, v129, v130
	v_mul_f32_e32 v130, v17, v17
	v_pk_mul_f32 v[18:19], v[18:19], v[132:133]
	v_fmac_f32_e32 v130, v16, v16
	v_add_f32_e32 v129, v130, v129
	v_mul_f32_e32 v130, v19, v19
	v_fmac_f32_e32 v130, v18, v18
	v_add_f32_e32 v129, v130, v129
	v_mov_b32_e32 v130, v129
	s_nop 1
	v_permlane16_swap_b32_e32 v130, v129
	v_add_f32_e32 v129, v129, v130
	v_mov_b32_e32 v130, v129
	s_nop 1
	v_permlane32_swap_b32_e32 v130, v129
	s_and_saveexec_b64 s[4:5], s[0:1]
	s_cbranch_execz .LBB0_895
	v_add_f32_e32 v129, v129, v130
	ds_write_b32 v223, v129 offset:5136
.LBB0_895:
	s_or_b64 exec, exec, s[4:5]
	v_mul_f32_e32 v129, 0x4b800000, v128
	v_cndmask_b32_e32 v128, v128, v129, vcc
	v_rsq_f32_e32 v128, v128
	s_nop 0
	v_mul_f32_e32 v129, 0x45800000, v128
	v_cndmask_b32_e32 v140, v128, v129, vcc
	v_pk_mul_f32 v[130:131], v[14:15], v[140:141] op_sel_hi:[1,0]
	v_pk_mul_f32 v[134:135], v[12:13], v[140:141] op_sel_hi:[1,0]
	v_pk_mul_f32 v[132:133], v[8:9], v[140:141] op_sel_hi:[1,0]
	v_mul_f32_e32 v8, v135, v135
	v_mul_f32_e32 v9, v131, v131
	v_fmac_f32_e32 v8, v134, v134
	v_fmac_f32_e32 v9, v130, v130
	v_add_f32_e32 v8, v8, v9
	v_mul_f32_e32 v9, v133, v133
	v_pk_mul_f32 v[128:129], v[10:11], v[140:141] op_sel_hi:[1,0]
	v_fmac_f32_e32 v9, v132, v132
	v_add_f32_e32 v8, v9, v8
	v_mul_f32_e32 v9, v129, v129
	v_fmac_f32_e32 v9, v128, v128
	v_add_f32_e32 v8, v9, v8
	v_mov_b32_e32 v9, v8
	s_nop 1
	v_permlane16_swap_b32_e32 v9, v8
	v_add_f32_e32 v8, v8, v9
	v_mov_b32_e32 v9, v8
	s_nop 1
	v_permlane32_swap_b32_e32 v9, v8
	s_and_saveexec_b64 s[4:5], s[0:1]
	s_cbranch_execz .LBB0_897
	v_add_f32_e32 v8, v8, v9
	ds_write_b32 v223, v8 offset:5632
.LBB0_897:
	s_or_b64 exec, exec, s[4:5]
	v_mov_b32_e32 v141, v140
	v_mov_b32_e32 v8, v140
	v_mov_b32_e32 v9, v140
	v_pk_mul_f32 v[138:139], v[6:7], v[8:9]
	v_pk_mul_f32 v[142:143], v[4:5], v[140:141]
	v_pk_mul_f32 v[140:141], v[0:1], v[140:141]
	v_mul_f32_e32 v0, v143, v143
	v_mul_f32_e32 v1, v139, v139
	v_fmac_f32_e32 v0, v142, v142
	v_fmac_f32_e32 v1, v138, v138
	v_add_f32_e32 v0, v0, v1
	v_mul_f32_e32 v1, v141, v141
	v_pk_mul_f32 v[136:137], v[2:3], v[8:9]
	v_fmac_f32_e32 v1, v140, v140
	v_add_f32_e32 v0, v1, v0
	v_mul_f32_e32 v1, v137, v137
	v_fmac_f32_e32 v1, v136, v136
	v_add_f32_e32 v0, v1, v0
	v_mov_b32_e32 v1, v0
	s_nop 1
	v_permlane16_swap_b32_e32 v1, v0
	v_add_f32_e32 v0, v0, v1
	v_mov_b32_e32 v1, v0
	s_nop 1
	v_permlane32_swap_b32_e32 v1, v0
	s_and_saveexec_b64 s[4:5], s[0:1]
	s_cbranch_execz .LBB0_899
	v_add_f32_e32 v0, v0, v1
	ds_write_b32 v223, v0 offset:5648

; __device__ __forceinline__ u32x4 pack8(f32x4 a, f32x4 b) { u32x4 w; w.x = cvtpk(a[0], a[1]); w.y = cvtpk(a[2], a[3]); w.z = cvtpk(b[0], b[1]); w.w = cvtpk(b[2], b[3]); return w; }
; #define FOR_BJ _Pragma("unroll") for (int bj = 0; bj < 2; ++bj)
;     __device__ __forceinline__ void operator()(f32x4 (&acc)[2][2][4][2], const Unit& u, int wr, int wc, int fr, int fq) const {
; #pragma unroll
;         for (int ai = 0; ai < 2; ++ai) {
;             u32x4 hr[4][2];
; #pragma unroll
;             for (int m = 0; m < 4; ++m) FOR_BJ { const unsigned off = (unsigned)(u.pm * BM + ai * HALF + wr * 64 + m * 16 + fr) * DM + u.pn * BM + 128 * bj + 32 * wc + 8 * fq; hr[m][bj] = *(const u32x4*)(H2B + off); }
; #pragma unroll
;             for (int m = 0; m < 4; ++m) FOR_BJ { const unsigned off = (unsigned)(u.pm * BM + ai * HALF + wr * 64 + m * 16 + fr) * DM + u.pn * BM + 128 * bj + 32 * wc + 8 * fq;
;                 const u32x4 h = hr[m][bj];
;                 const f32x4 v0 = acc[ai][bj][m][0] + (f32x4){bflo(h.x), bfhi(h.x), bflo(h.y), bfhi(h.y)}, v1 = acc[ai][bj][m][1] + (f32x4){bflo(h.z), bfhi(h.z), bflo(h.w), bfhi(h.w)};
;                 acc[ai][bj][m][0] = v0; acc[ai][bj][m][1] = v1;
;                 *(u32x4*)(H2B + off) = pack8(v0, v1); }
;             asm volatile("" ::: "memory");
.LBB0_1049:
	v_lshl_add_u32 v146, s42, 8, v160
	v_lshl_or_b32 v128, s8, 8, v162
	v_lshl_add_u32 v140, v146, 11, v128
	s_waitcnt vmcnt(0)
	v_lshl_add_u64 v[192:193], v[140:141], 1, s[88:89]
	v_mov_b32_e32 v129, v141
	v_or_b32_e32 v128, 0x80, v140
	global_load_dwordx4 v[148:151], v[192:193], off
	v_lshl_add_u64 v[194:195], v[128:129], 1, s[88:89]
	v_add_u32_e32 v128, 0x8000, v140
	global_load_dwordx4 v[152:155], v[194:195], off
	v_lshl_add_u64 v[196:197], v[128:129], 1, s[88:89]
	global_load_dwordx4 v[168:171], v[196:197], off
	v_add_u32_e32 v128, 0x8080, v140
	v_lshl_add_u64 v[198:199], v[128:129], 1, s[88:89]
	global_load_dwordx4 v[172:175], v[198:199], off
	v_add_u32_e32 v128, 0x10000, v140
	v_lshl_add_u64 v[200:201], v[128:129], 1, s[88:89]
	global_load_dwordx4 v[180:183], v[200:201], off
	v_mov_b32_e32 v131, v141
	v_add_u32_e32 v130, 0x10080, v140
	v_mov_b32_e32 v157, v141
	v_add_u32_e32 v128, 0x18000, v140
	v_add_u32_e32 v156, 0x18080, v140
	v_lshl_add_u64 v[202:203], v[130:131], 1, s[88:89]
	v_lshl_add_u64 v[158:159], v[128:129], 1, s[88:89]
	v_lshl_add_u64 v[156:157], v[156:157], 1, s[88:89]
	global_load_dwordx4 v[184:187], v[202:203], off
	global_load_dwordx4 v[188:191], v[158:159], off
	global_load_dwordx4 v[128:131], v[156:157], off
	s_waitcnt vmcnt(0)
	v_lshlrev_b32_e32 v204, 16, v148
	v_and_b32_e32 v205, 0xffff0000, v148
	v_lshlrev_b32_e32 v148, 16, v149
	v_and_b32_e32 v149, 0xffff0000, v149
	v_lshlrev_b32_e32 v206, 16, v150
	v_and_b32_e32 v207, 0xffff0000, v150
	v_lshlrev_b32_e32 v150, 16, v151
	v_and_b32_e32 v151, 0xffff0000, v151
	v_pk_add_f32 v[126:127], v[126:127], v[148:149]
	v_pk_add_f32 v[124:125], v[124:125], v[204:205]
	v_pk_add_f32 v[122:123], v[122:123], v[150:151]
	v_pk_add_f32 v[120:121], v[120:121], v[206:207]
	v_lshlrev_b32_e32 v148, 16, v152
	v_and_b32_e32 v149, 0xffff0000, v152
	v_lshlrev_b32_e32 v150, 16, v153
	v_and_b32_e32 v151, 0xffff0000, v153
	v_lshlrev_b32_e32 v204, 16, v154
	v_and_b32_e32 v205, 0xffff0000, v154
	v_lshlrev_b32_e32 v206, 16, v155
	v_and_b32_e32 v207, 0xffff0000, v155
	v_lshlrev_b32_e32 v208, 16, v168
	v_and_b32_e32 v209, 0xffff0000, v168
	v_lshlrev_b32_e32 v210, 16, v169
	v_and_b32_e32 v211, 0xffff0000, v169
	v_lshlrev_b32_e32 v212, 16, v170
	v_and_b32_e32 v213, 0xffff0000, v170
	v_lshlrev_b32_e32 v214, 16, v171
	v_and_b32_e32 v215, 0xffff0000, v171
	v_pk_add_f32 v[152:153], v[110:111], v[150:151]
	v_pk_add_f32 v[154:155], v[108:109], v[148:149]
	v_pk_add_f32 v[148:149], v[106:107], v[206:207]
	v_pk_add_f32 v[150:151], v[104:105], v[204:205]
	v_cvt_pk_bf16_f32 v168, v124, v125
	v_cvt_pk_bf16_f32 v169, v126, v127
	v_cvt_pk_bf16_f32 v170, v120, v121
	v_cvt_pk_bf16_f32 v171, v122, v123
	v_pk_add_f32 v[108:109], v[118:119], v[210:211]
	v_pk_add_f32 v[116:117], v[116:117], v[208:209]
	v_pk_add_f32 v[104:105], v[114:115], v[214:215]
	v_pk_add_f32 v[106:107], v[112:113], v[212:213]
	v_cvt_pk_bf16_f32 v110, v154, v155
	v_cvt_pk_bf16_f32 v111, v152, v153
	v_cvt_pk_bf16_f32 v112, v150, v151
	v_cvt_pk_bf16_f32 v113, v148, v149
	v_lshlrev_b32_e32 v216, 16, v172
	v_and_b32_e32 v217, 0xffff0000, v172
	v_lshlrev_b32_e32 v172, 16, v173
	global_store_dwordx4 v[192:193], v[168:171], off
	v_and_b32_e32 v173, 0xffff0000, v173
	v_pk_add_f32 v[102:103], v[102:103], v[172:173]
	v_cvt_pk_bf16_f32 v168, v116, v117
	v_cvt_pk_bf16_f32 v169, v108, v109
	v_cvt_pk_bf16_f32 v170, v106, v107
	v_cvt_pk_bf16_f32 v171, v104, v105
	global_store_dwordx4 v[194:195], v[110:113], off
	global_store_dwordx4 v[196:197], v[168:171], off
	v_pk_add_f32 v[100:101], v[100:101], v[216:217]
	v_lshlrev_b32_e32 v110, 16, v174
	v_and_b32_e32 v111, 0xffff0000, v174
	v_lshlrev_b32_e32 v112, 16, v175
	v_and_b32_e32 v113, 0xffff0000, v175
	v_pk_add_f32 v[94:95], v[94:95], v[112:113]
	v_pk_add_f32 v[110:111], v[92:93], v[110:111]
	v_cvt_pk_bf16_f32 v112, v100, v101
	v_cvt_pk_bf16_f32 v113, v102, v103
	v_cvt_pk_bf16_f32 v114, v110, v111
	v_cvt_pk_bf16_f32 v115, v94, v95
	global_store_dwordx4 v[198:199], v[112:115], off
	v_lshlrev_b32_e32 v92, 16, v181
	v_and_b32_e32 v93, 0xffff0000, v181
	v_lshlrev_b32_e32 v112, 16, v180
	v_and_b32_e32 v113, 0xffff0000, v180
	v_pk_add_f32 v[92:93], v[98:99], v[92:93]
	v_pk_add_f32 v[96:97], v[96:97], v[112:113]
	v_lshlrev_b32_e32 v98, 16, v182
	v_and_b32_e32 v99, 0xffff0000, v182
	v_lshlrev_b32_e32 v112, 16, v183
	v_and_b32_e32 v113, 0xffff0000, v183
	v_pk_add_f32 v[90:91], v[90:91], v[112:113]
	v_pk_add_f32 v[88:89], v[88:89], v[98:99]
	v_cvt_pk_bf16_f32 v112, v96, v97
	v_cvt_pk_bf16_f32 v113, v92, v93
	v_cvt_pk_bf16_f32 v114, v88, v89
	v_cvt_pk_bf16_f32 v115, v90, v91
	global_store_dwordx4 v[200:201], v[112:115], off
	v_lshlrev_b32_e32 v98, 16, v184
	v_and_b32_e32 v99, 0xffff0000, v184
	v_lshlrev_b32_e32 v112, 16, v185
	v_and_b32_e32 v113, 0xffff0000, v185
	v_pk_add_f32 v[86:87], v[86:87], v[112:113]
	v_pk_add_f32 v[84:85], v[84:85], v[98:99]
	v_lshlrev_b32_e32 v98, 16, v186
	v_and_b32_e32 v99, 0xffff0000, v186
	v_lshlrev_b32_e32 v112, 16, v187
	v_and_b32_e32 v113, 0xffff0000, v187
	v_pk_add_f32 v[78:79], v[78:79], v[112:113]
	v_pk_add_f32 v[98:99], v[76:77], v[98:99]
	v_cvt_pk_bf16_f32 v112, v84, v85
	v_cvt_pk_bf16_f32 v113, v86, v87
	v_cvt_pk_bf16_f32 v114, v98, v99
	v_cvt_pk_bf16_f32 v115, v78, v79
	global_store_dwordx4 v[202:203], v[112:115], off
	v_lshlrev_b32_e32 v76, 16, v189
	v_and_b32_e32 v77, 0xffff0000, v189
	v_lshlrev_b32_e32 v112, 16, v188
	v_and_b32_e32 v113, 0xffff0000, v188
	v_pk_add_f32 v[76:77], v[82:83], v[76:77]
	v_pk_add_f32 v[80:81], v[80:81], v[112:113]
	v_lshlrev_b32_e32 v82, 16, v190
	v_and_b32_e32 v83, 0xffff0000, v190
	v_lshlrev_b32_e32 v112, 16, v191
	v_and_b32_e32 v113, 0xffff0000, v191
; __device__ __forceinline__ u32x4 pack8(f32x4 a, f32x4 b) { u32x4 w; w.x = cvtpk(a[0], a[1]); w.y = cvtpk(a[2], a[3]); w.z = cvtpk(b[0], b[1]); w.w = cvtpk(b[2], b[3]); return w; }
; #define FOR_BJ _Pragma("unroll") for (int bj = 0; bj < 2; ++bj)
;     __device__ __forceinline__ void operator()(f32x4 (&acc)[2][2][4][2], const Unit& u, int wr, int wc, int fr, int fq) const {
; #pragma unroll
;         for (int ai = 0; ai < 2; ++ai) {
;             u32x4 hr[4][2];
; #pragma unroll
;             for (int m = 0; m < 4; ++m) FOR_BJ { const unsigned off = (unsigned)(u.pm * BM + ai * HALF + wr * 64 + m * 16 + fr) * DM + u.pn * BM + 128 * bj + 32 * wc + 8 * fq; hr[m][bj] = *(const u32x4*)(H2B + off); }
; #pragma unroll
;             for (int m = 0; m < 4; ++m) FOR_BJ { const unsigned off = (unsigned)(u.pm * BM + ai * HALF + wr * 64 + m * 16 + fr) * DM + u.pn * BM + 128 * bj + 32 * wc + 8 * fq;
;                 const u32x4 h = hr[m][bj];
;                 const f32x4 v0 = acc[ai][bj][m][0] + (f32x4){bflo(h.x), bfhi(h.x), bflo(h.y), bfhi(h.y)}, v1 = acc[ai][bj][m][1] + (f32x4){bflo(h.z), bfhi(h.z), bflo(h.w), bfhi(h.w)};
;                 acc[ai][bj][m][0] = v0; acc[ai][bj][m][1] = v1;
;                 *(u32x4*)(H2B + off) = pack8(v0, v1); }
;             asm volatile("" ::: "memory");
	v_pk_add_f32 v[74:75], v[74:75], v[112:113]
	v_pk_add_f32 v[72:73], v[72:73], v[82:83]
	v_cvt_pk_bf16_f32 v112, v80, v81
	v_cvt_pk_bf16_f32 v113, v76, v77
	v_cvt_pk_bf16_f32 v114, v72, v73
	v_cvt_pk_bf16_f32 v115, v74, v75
	global_store_dwordx4 v[158:159], v[112:115], off
	v_lshlrev_b32_e32 v82, 16, v128
	v_and_b32_e32 v83, 0xffff0000, v128
	v_lshlrev_b32_e32 v112, 16, v129
	v_and_b32_e32 v113, 0xffff0000, v129
	v_pk_add_f32 v[70:71], v[70:71], v[112:113]
	v_pk_add_f32 v[68:69], v[68:69], v[82:83]
	v_lshlrev_b32_e32 v82, 16, v130
	v_and_b32_e32 v83, 0xffff0000, v130
	v_lshlrev_b32_e32 v112, 16, v131
	v_and_b32_e32 v113, 0xffff0000, v131
	v_pk_add_f32 v[66:67], v[66:67], v[112:113]
	v_pk_add_f32 v[64:65], v[64:65], v[82:83]
	v_cvt_pk_bf16_f32 v112, v68, v69
	v_cvt_pk_bf16_f32 v113, v70, v71
	v_cvt_pk_bf16_f32 v114, v64, v65
	v_cvt_pk_bf16_f32 v115, v66, v67
	global_store_dwordx4 v[156:157], v[112:115], off
	v_add_u32_e32 v82, 0x40000, v140
	v_mov_b32_e32 v83, v141
	v_lshl_add_u64 v[82:83], v[82:83], 1, s[88:89]
	global_load_dwordx4 v[128:131], v[82:83], off
	v_add_u32_e32 v112, 0x40080, v140
	v_mov_b32_e32 v113, v141
	v_lshl_add_u64 v[114:115], v[112:113], 1, s[88:89]
	global_load_dwordx4 v[156:159], v[114:115], off
	v_add_u32_e32 v112, 0x48000, v140
	v_lshl_add_u64 v[118:119], v[112:113], 1, s[88:89]
	global_load_dwordx4 v[168:171], v[118:119], off
	v_add_u32_e32 v112, 0x48080, v140
	v_lshl_add_u64 v[196:197], v[112:113], 1, s[88:89]
	global_load_dwordx4 v[172:175], v[196:197], off
	v_add_u32_e32 v112, 0x50000, v140
	v_lshl_add_u64 v[198:199], v[112:113], 1, s[88:89]
	global_load_dwordx4 v[180:183], v[198:199], off
	v_add_u32_e32 v112, 0x50080, v140
	v_lshl_add_u64 v[200:201], v[112:113], 1, s[88:89]
	global_load_dwordx4 v[184:187], v[200:201], off
	v_add_u32_e32 v112, 0x58000, v140
	v_lshl_add_u64 v[202:203], v[112:113], 1, s[88:89]
	v_add_u32_e32 v140, 0x58080, v140
	v_lshl_add_u64 v[112:113], v[140:141], 1, s[88:89]
	global_load_dwordx4 v[188:191], v[202:203], off
	global_load_dwordx4 v[192:195], v[112:113], off
	s_waitcnt vmcnt(7)
	v_lshlrev_b32_e32 v204, 16, v128
	v_and_b32_e32 v205, 0xffff0000, v128
	v_lshlrev_b32_e32 v128, 16, v129
	v_and_b32_e32 v129, 0xffff0000, v129
	v_pk_add_f32 v[62:63], v[62:63], v[128:129]
	v_lshlrev_b32_e32 v128, 16, v130
	v_and_b32_e32 v129, 0xffff0000, v130
	v_lshlrev_b32_e32 v130, 16, v131
	v_and_b32_e32 v131, 0xffff0000, v131
	v_pk_add_f32 v[60:61], v[60:61], v[204:205]
	v_pk_add_f32 v[58:59], v[58:59], v[130:131]
	v_pk_add_f32 v[56:57], v[56:57], v[128:129]
	v_cvt_pk_bf16_f32 v128, v60, v61
	v_cvt_pk_bf16_f32 v129, v62, v63
	v_cvt_pk_bf16_f32 v130, v56, v57
	v_cvt_pk_bf16_f32 v131, v58, v59
	global_store_dwordx4 v[82:83], v[128:131], off
	s_waitcnt vmcnt(7)
	v_lshlrev_b32_e32 v82, 16, v156
	v_and_b32_e32 v83, 0xffff0000, v156
	v_lshlrev_b32_e32 v128, 16, v157
	v_and_b32_e32 v129, 0xffff0000, v157
	v_pk_add_f32 v[54:55], v[54:55], v[128:129]
	v_pk_add_f32 v[52:53], v[52:53], v[82:83]
	v_lshlrev_b32_e32 v82, 16, v158
	v_and_b32_e32 v83, 0xffff0000, v158
	v_lshlrev_b32_e32 v128, 16, v159
	v_and_b32_e32 v129, 0xffff0000, v159
	v_pk_add_f32 v[46:47], v[46:47], v[128:129]
	v_pk_add_f32 v[82:83], v[44:45], v[82:83]
	v_cvt_pk_bf16_f32 v128, v52, v53
	v_cvt_pk_bf16_f32 v129, v54, v55
	v_cvt_pk_bf16_f32 v130, v82, v83
	v_cvt_pk_bf16_f32 v131, v46, v47
	global_store_dwordx4 v[114:115], v[128:131], off
	s_waitcnt vmcnt(7)
	v_lshlrev_b32_e32 v114, 16, v168
	v_and_b32_e32 v115, 0xffff0000, v168
	v_lshlrev_b32_e32 v44, 16, v169
	v_and_b32_e32 v45, 0xffff0000, v169
	v_pk_add_f32 v[44:45], v[50:51], v[44:45]
	v_pk_add_f32 v[48:49], v[48:49], v[114:115]
	v_lshlrev_b32_e32 v50, 16, v170
	v_and_b32_e32 v51, 0xffff0000, v170
	v_lshlrev_b32_e32 v114, 16, v171
	v_and_b32_e32 v115, 0xffff0000, v171
	v_pk_add_f32 v[42:43], v[42:43], v[114:115]
	v_pk_add_f32 v[40:41], v[40:41], v[50:51]
	s_waitcnt vmcnt(6)
	v_lshlrev_b32_e32 v50, 16, v172
	v_and_b32_e32 v51, 0xffff0000, v172
	v_lshlrev_b32_e32 v114, 16, v173
	v_and_b32_e32 v115, 0xffff0000, v173
	v_pk_add_f32 v[38:39], v[38:39], v[114:115]
	v_pk_add_f32 v[36:37], v[36:37], v[50:51]
	v_lshlrev_b32_e32 v50, 16, v174
	v_and_b32_e32 v51, 0xffff0000, v174
	v_lshlrev_b32_e32 v114, 16, v175
	v_and_b32_e32 v115, 0xffff0000, v175
	v_pk_add_f32 v[30:31], v[30:31], v[114:115]
	v_pk_add_f32 v[50:51], v[28:29], v[50:51]
	s_waitcnt vmcnt(5)
	v_lshlrev_b32_e32 v114, 16, v180
	v_and_b32_e32 v115, 0xffff0000, v180
	v_lshlrev_b32_e32 v28, 16, v181
	v_and_b32_e32 v29, 0xffff0000, v181
	v_pk_add_f32 v[28:29], v[34:35], v[28:29]
	v_pk_add_f32 v[32:33], v[32:33], v[114:115]
	v_lshlrev_b32_e32 v34, 16, v182
	v_and_b32_e32 v35, 0xffff0000, v182
	v_lshlrev_b32_e32 v114, 16, v183
	v_and_b32_e32 v115, 0xffff0000, v183
	v_pk_add_f32 v[26:27], v[26:27], v[114:115]
	v_pk_add_f32 v[24:25], v[24:25], v[34:35]
	s_waitcnt vmcnt(4)
	v_lshlrev_b32_e32 v34, 16, v184
	v_and_b32_e32 v35, 0xffff0000, v184
	v_lshlrev_b32_e32 v114, 16, v185
	v_and_b32_e32 v115, 0xffff0000, v185
	v_pk_add_f32 v[22:23], v[22:23], v[114:115]
	v_pk_add_f32 v[20:21], v[20:21], v[34:35]
	v_lshlrev_b32_e32 v34, 16, v186
	v_and_b32_e32 v35, 0xffff0000, v186
	v_lshlrev_b32_e32 v114, 16, v187
	v_and_b32_e32 v115, 0xffff0000, v187
	v_cvt_pk_bf16_f32 v128, v48, v49
	v_cvt_pk_bf16_f32 v129, v44, v45
	v_cvt_pk_bf16_f32 v130, v40, v41
	v_cvt_pk_bf16_f32 v131, v42, v43
	v_pk_add_f32 v[14:15], v[14:15], v[114:115]
	v_pk_add_f32 v[34:35], v[12:13], v[34:35]
	s_waitcnt vmcnt(3)
; __device__ __forceinline__ u32x4 pack8(f32x4 a, f32x4 b) { u32x4 w; w.x = cvtpk(a[0], a[1]); w.y = cvtpk(a[2], a[3]); w.z = cvtpk(b[0], b[1]); w.w = cvtpk(b[2], b[3]); return w; }
; #define FOR_BJ _Pragma("unroll") for (int bj = 0; bj < 2; ++bj)
; __device__ __forceinline__ void head_ss(const f32x4 (&v)[2][2][4][2], float (&tot)[2][4][2], LAS float* X, int wr, int wc, int fr, int fq) {
;     ...
;                 const f32x4 a = v[ai][bj][m][0], b = v[ai][bj][m][1];
;                 float s = (a[0] * a[0] + a[1] * a[1]) + (a[2] * a[2] + a[3] * a[3]) + (b[0] * b[0] + b[1] * b[1]) + (b[2] * b[2] + b[3] * b[3]);
;                 s += __shfl_xor(s, 16); s += __shfl_xor(s, 32);
;                 if (fq == 0) X[((ai * 128 + wr * 64 + m * 16 + fr) * 2 + bj) * 4 + wc] = s;
;     __device__ __forceinline__ void operator()(f32x4 (&acc)[2][2][4][2], const Unit& u, int wr, int wc, int fr, int fq) const {
;     ...
;             for (int m = 0; m < 4; ++m) FOR_BJ { const unsigned off = (unsigned)(u.pm * BM + ai * HALF + wr * 64 + m * 16 + fr) * DM + u.pn * BM + 128 * bj + 32 * wc + 8 * fq;
;                 const u32x4 h = hr[m][bj];
;                 const f32x4 v0 = acc[ai][bj][m][0] + (f32x4){bflo(h.x), bfhi(h.x), bflo(h.y), bfhi(h.y)}, v1 = acc[ai][bj][m][1] + (f32x4){bflo(h.z), bfhi(h.z), bflo(h.w), bfhi(h.w)};
;                 acc[ai][bj][m][0] = v0; acc[ai][bj][m][1] = v1;
;                 *(u32x4*)(H2B + off) = pack8(v0, v1); }
;             asm volatile("" ::: "memory");
	v_lshlrev_b32_e32 v114, 16, v188
	v_and_b32_e32 v115, 0xffff0000, v188
	v_lshlrev_b32_e32 v12, 16, v189
	v_and_b32_e32 v13, 0xffff0000, v189
	global_store_dwordx4 v[118:119], v[128:131], off
	v_pk_add_f32 v[12:13], v[18:19], v[12:13]
	v_pk_add_f32 v[16:17], v[16:17], v[114:115]
	v_cvt_pk_bf16_f32 v128, v36, v37
	v_cvt_pk_bf16_f32 v129, v38, v39
	v_cvt_pk_bf16_f32 v130, v50, v51
	v_cvt_pk_bf16_f32 v131, v30, v31
	v_lshlrev_b32_e32 v18, 16, v190
	v_and_b32_e32 v19, 0xffff0000, v190
	v_lshlrev_b32_e32 v114, 16, v191
	v_and_b32_e32 v115, 0xffff0000, v191
	global_store_dwordx4 v[196:197], v[128:131], off
	v_pk_add_f32 v[10:11], v[10:11], v[114:115]
	v_pk_add_f32 v[8:9], v[8:9], v[18:19]
	v_cvt_pk_bf16_f32 v128, v32, v33
	v_cvt_pk_bf16_f32 v129, v28, v29
	v_cvt_pk_bf16_f32 v130, v24, v25
	v_cvt_pk_bf16_f32 v131, v26, v27
	s_waitcnt vmcnt(4)
	v_lshlrev_b32_e32 v18, 16, v192
	v_and_b32_e32 v19, 0xffff0000, v192
	v_lshlrev_b32_e32 v114, 16, v193
	v_and_b32_e32 v115, 0xffff0000, v193
	global_store_dwordx4 v[198:199], v[128:131], off
	v_pk_add_f32 v[6:7], v[6:7], v[114:115]
	v_pk_add_f32 v[4:5], v[4:5], v[18:19]
	v_cvt_pk_bf16_f32 v128, v20, v21
	v_cvt_pk_bf16_f32 v129, v22, v23
	v_cvt_pk_bf16_f32 v130, v34, v35
	v_cvt_pk_bf16_f32 v131, v14, v15
	v_lshlrev_b32_e32 v18, 16, v194
	v_and_b32_e32 v19, 0xffff0000, v194
	v_lshlrev_b32_e32 v114, 16, v195
	v_and_b32_e32 v115, 0xffff0000, v195
	global_store_dwordx4 v[200:201], v[128:131], off
	v_pk_add_f32 v[2:3], v[2:3], v[114:115]
	v_pk_add_f32 v[0:1], v[0:1], v[18:19]
	v_cvt_pk_bf16_f32 v128, v16, v17
	v_cvt_pk_bf16_f32 v129, v12, v13
	v_cvt_pk_bf16_f32 v130, v8, v9
	v_cvt_pk_bf16_f32 v131, v10, v11
	global_store_dwordx4 v[202:203], v[128:131], off
	v_and_b32_e32 v19, 64, v167
	v_xor_b32_e32 v18, 16, v167
	v_cvt_pk_bf16_f32 v128, v4, v5
	v_cvt_pk_bf16_f32 v129, v6, v7
	v_cvt_pk_bf16_f32 v130, v0, v1
	v_cvt_pk_bf16_f32 v131, v2, v3
	global_store_dwordx4 v[112:113], v[128:131], off
	v_mul_f32_e32 v112, v125, v125
	v_mul_f32_e32 v113, v127, v127
	v_fmac_f32_e32 v112, v124, v124
	v_fmac_f32_e32 v113, v126, v126
	v_add_f32_e32 v112, v112, v113
	v_mul_f32_e32 v113, v121, v121
	v_add_u32_e32 v19, 64, v19
	v_fmac_f32_e32 v113, v120, v120
	v_cmp_lt_i32_e32 vcc, v18, v19
	v_add_f32_e32 v112, v113, v112
	v_mul_f32_e32 v113, v123, v123
	v_cndmask_b32_e32 v18, v167, v18, vcc
	v_fmac_f32_e32 v113, v122, v122
	v_lshlrev_b32_e32 v18, 2, v18
	v_add_f32_e32 v113, v113, v112
	v_mov_b32_e32 v114, v113
	s_nop 1
	v_permlane16_swap_b32_e32 v114, v113
	v_xor_b32_e32 v112, 32, v167
	v_cmp_lt_i32_e32 vcc, v112, v19
	v_add_f32_e32 v113, v113, v114
	v_cndmask_b32_e32 v19, v167, v112, vcc
	v_lshlrev_b32_e32 v112, 2, v19
	v_mov_b32_e32 v114, v113
	s_nop 1
	v_permlane32_swap_b32_e32 v114, v113
	v_add_u32_e32 v19, s58, v163
	s_and_saveexec_b64 s[42:43], s[0:1]
	s_cbranch_execz .LBB0_1051
	v_add_f32_e32 v113, v113, v114
	ds_write_b32 v19, v113
.LBB0_1051:
	s_or_b64 exec, exec, s[42:43]
	v_mul_f32_e32 v113, v155, v155
	v_mul_f32_e32 v114, v153, v153
	v_fmac_f32_e32 v113, v154, v154
	v_fmac_f32_e32 v114, v152, v152
	v_add_f32_e32 v113, v113, v114
	v_mul_f32_e32 v114, v151, v151
	v_fmac_f32_e32 v114, v150, v150
	v_add_f32_e32 v113, v114, v113
	v_mul_f32_e32 v114, v149, v149
	v_fmac_f32_e32 v114, v148, v148
	v_add_f32_e32 v113, v114, v113
	v_mov_b32_e32 v114, v113
	s_nop 1
	v_permlane16_swap_b32_e32 v114, v113
	v_add_f32_e32 v113, v113, v114
	v_mov_b32_e32 v114, v113
	s_nop 1
	v_permlane32_swap_b32_e32 v114, v113
	s_and_saveexec_b64 s[42:43], s[0:1]
	s_cbranch_execz .LBB0_1053
	v_add_f32_e32 v113, v113, v114
	ds_write_b32 v19, v113 offset:16
.LBB0_1053:
	s_or_b64 exec, exec, s[42:43]
	v_mul_f32_e32 v113, v117, v117
	v_mul_f32_e32 v109, v109, v109
	v_fmac_f32_e32 v113, v116, v116
	v_fmac_f32_e32 v109, v108, v108
	v_mul_f32_e32 v107, v107, v107
	v_add_f32_e32 v108, v113, v109
	v_fmac_f32_e32 v107, v106, v106
	v_mul_f32_e32 v105, v105, v105
	v_add_f32_e32 v106, v107, v108
	v_fmac_f32_e32 v105, v104, v104
	v_add_f32_e32 v104, v105, v106
	v_mov_b32_e32 v105, v104
	s_nop 1
	v_permlane16_swap_b32_e32 v105, v104
	v_add_f32_e32 v104, v104, v105
	v_mov_b32_e32 v105, v104
	s_nop 1
	v_permlane32_swap_b32_e32 v105, v104
	s_and_saveexec_b64 s[42:43], s[0:1]
	s_cbranch_execz .LBB0_1055
	v_add_f32_e32 v104, v104, v105
	ds_write_b32 v19, v104 offset:512
.LBB0_1055:
	s_or_b64 exec, exec, s[42:43]
	v_mul_f32_e32 v101, v101, v101
	v_fmac_f32_e32 v101, v100, v100
	v_mul_f32_e32 v100, v103, v103
	v_fmac_f32_e32 v100, v102, v102
	v_add_f32_e32 v100, v101, v100
	v_mul_f32_e32 v101, v111, v111
	v_fmac_f32_e32 v101, v110, v110
	v_mul_f32_e32 v95, v95, v95
	v_add_f32_e32 v100, v101, v100
	v_fmac_f32_e32 v95, v94, v94
	v_add_f32_e32 v94, v95, v100
	v_mov_b32_e32 v95, v94
	s_nop 1
	v_permlane16_swap_b32_e32 v95, v94
	v_add_f32_e32 v94, v94, v95
	v_mov_b32_e32 v95, v94
	s_nop 1
	v_permlane32_swap_b32_e32 v95, v94
	s_and_saveexec_b64 s[42:43], s[0:1]
	s_cbranch_execz .LBB0_1057
	v_add_f32_e32 v94, v94, v95
	ds_write_b32 v19, v94 offset:528
.LBB0_1057:
	s_or_b64 exec, exec, s[42:43]
	v_mul_f32_e32 v94, v97, v97
	v_mul_f32_e32 v93, v93, v93
	v_fmac_f32_e32 v94, v96, v96
	v_fmac_f32_e32 v93, v92, v92
	v_mul_f32_e32 v89, v89, v89
	v_add_f32_e32 v92, v94, v93
	v_fmac_f32_e32 v89, v88, v88
	v_add_f32_e32 v88, v89, v92
	v_mul_f32_e32 v89, v91, v91
	v_fmac_f32_e32 v89, v90, v90
	v_add_f32_e32 v88, v89, v88
	v_mov_b32_e32 v89, v88
	s_nop 1
	v_permlane16_swap_b32_e32 v89, v88
	v_add_f32_e32 v88, v88, v89
	v_mov_b32_e32 v89, v88
	s_nop 1
	v_permlane32_swap_b32_e32 v89, v88
	s_and_saveexec_b64 s[42:43], s[0:1]
	s_cbranch_execz .LBB0_1059
	v_add_f32_e32 v88, v88, v89
	ds_write_b32 v19, v88 offset:1024
; __device__ __forceinline__ void head_ss(const f32x4 (&v)[2][2][4][2], float (&tot)[2][4][2], LAS float* X, int wr, int wc, int fr, int fq) {
;     ...
;                 const f32x4 a = v[ai][bj][m][0], b = v[ai][bj][m][1];
;                 float s = (a[0] * a[0] + a[1] * a[1]) + (a[2] * a[2] + a[3] * a[3]) + (b[0] * b[0] + b[1] * b[1]) + (b[2] * b[2] + b[3] * b[3]);
;                 s += __shfl_xor(s, 16); s += __shfl_xor(s, 32);
;                 if (fq == 0) X[((ai * 128 + wr * 64 + m * 16 + fr) * 2 + bj) * 4 + wc] = s;
;             }
.LBB0_1059:
	s_or_b64 exec, exec, s[42:43]
	v_mul_f32_e32 v85, v85, v85
	v_fmac_f32_e32 v85, v84, v84
	v_mul_f32_e32 v84, v87, v87
	v_fmac_f32_e32 v84, v86, v86
	v_add_f32_e32 v84, v85, v84
	v_mul_f32_e32 v85, v99, v99
	v_fmac_f32_e32 v85, v98, v98
	v_mul_f32_e32 v79, v79, v79
	v_add_f32_e32 v84, v85, v84
	v_fmac_f32_e32 v79, v78, v78
	v_add_f32_e32 v78, v79, v84
	v_mov_b32_e32 v79, v78
	s_nop 1
	v_permlane16_swap_b32_e32 v79, v78
	v_add_f32_e32 v78, v78, v79
	v_mov_b32_e32 v79, v78
	s_nop 1
	v_permlane32_swap_b32_e32 v79, v78
	s_and_saveexec_b64 s[42:43], s[0:1]
	s_cbranch_execz .LBB0_1061
	v_add_f32_e32 v78, v78, v79
	ds_write_b32 v19, v78 offset:1040
.LBB0_1061:
	s_or_b64 exec, exec, s[42:43]
	v_mul_f32_e32 v78, v81, v81
	v_mul_f32_e32 v77, v77, v77
	v_fmac_f32_e32 v78, v80, v80
	v_fmac_f32_e32 v77, v76, v76
	v_mul_f32_e32 v73, v73, v73
	v_add_f32_e32 v76, v78, v77
	v_fmac_f32_e32 v73, v72, v72
	v_add_f32_e32 v72, v73, v76
	v_mul_f32_e32 v73, v75, v75
	v_fmac_f32_e32 v73, v74, v74
	v_add_f32_e32 v72, v73, v72
	v_mov_b32_e32 v73, v72
	s_nop 1
	v_permlane16_swap_b32_e32 v73, v72
	v_add_f32_e32 v72, v72, v73
	v_mov_b32_e32 v73, v72
	s_nop 1
	v_permlane32_swap_b32_e32 v73, v72
	s_and_saveexec_b64 s[42:43], s[0:1]
	s_cbranch_execz .LBB0_1063
	v_add_f32_e32 v72, v72, v73
	ds_write_b32 v19, v72 offset:1536
.LBB0_1063:
	s_or_b64 exec, exec, s[42:43]
	v_mul_f32_e32 v69, v69, v69
	v_fmac_f32_e32 v69, v68, v68
	v_mul_f32_e32 v68, v71, v71
	v_fmac_f32_e32 v68, v70, v70
	v_mul_f32_e32 v65, v65, v65
	v_add_f32_e32 v68, v69, v68
	v_fmac_f32_e32 v65, v64, v64
	v_add_f32_e32 v64, v65, v68
	v_mul_f32_e32 v65, v67, v67
	v_fmac_f32_e32 v65, v66, v66
	v_add_f32_e32 v64, v65, v64
	v_mov_b32_e32 v65, v64
	s_nop 1
	v_permlane16_swap_b32_e32 v65, v64
	v_add_f32_e32 v64, v64, v65
	v_mov_b32_e32 v65, v64
	s_nop 1
	v_permlane32_swap_b32_e32 v65, v64
	s_and_saveexec_b64 s[42:43], s[0:1]
	s_cbranch_execz .LBB0_1065
	v_add_f32_e32 v64, v64, v65
	ds_write_b32 v19, v64 offset:1552
.LBB0_1065:
	s_or_b64 exec, exec, s[42:43]
	v_mul_f32_e32 v61, v61, v61
	v_fmac_f32_e32 v61, v60, v60
	v_mul_f32_e32 v60, v63, v63
	v_fmac_f32_e32 v60, v62, v62
	v_mul_f32_e32 v57, v57, v57
	v_add_f32_e32 v60, v61, v60
	v_fmac_f32_e32 v57, v56, v56
	v_add_f32_e32 v56, v57, v60
	v_mul_f32_e32 v57, v59, v59
	v_fmac_f32_e32 v57, v58, v58
	v_add_f32_e32 v56, v57, v56
	v_mov_b32_e32 v57, v56
	s_nop 1
	v_permlane16_swap_b32_e32 v57, v56
	v_add_f32_e32 v56, v56, v57
	v_mov_b32_e32 v57, v56
	s_nop 1
	v_permlane32_swap_b32_e32 v57, v56
	s_and_saveexec_b64 s[42:43], s[0:1]
	s_cbranch_execz .LBB0_1067
	v_add_f32_e32 v56, v56, v57
	ds_write_b32 v19, v56 offset:4096
.LBB0_1067:
	s_or_b64 exec, exec, s[42:43]
	v_mul_f32_e32 v53, v53, v53
	v_fmac_f32_e32 v53, v52, v52
	v_mul_f32_e32 v52, v55, v55
	v_fmac_f32_e32 v52, v54, v54
	v_add_f32_e32 v52, v53, v52
	v_mul_f32_e32 v53, v83, v83
	v_fmac_f32_e32 v53, v82, v82
	v_mul_f32_e32 v47, v47, v47
	v_add_f32_e32 v52, v53, v52
	v_fmac_f32_e32 v47, v46, v46
	v_add_f32_e32 v46, v47, v52
	v_mov_b32_e32 v47, v46
	s_nop 1
	v_permlane16_swap_b32_e32 v47, v46
	v_add_f32_e32 v46, v46, v47
	v_mov_b32_e32 v47, v46
	s_nop 1
	v_permlane32_swap_b32_e32 v47, v46
	s_and_saveexec_b64 s[42:43], s[0:1]
	s_cbranch_execz .LBB0_1069
	v_add_f32_e32 v46, v46, v47
	ds_write_b32 v19, v46 offset:4112
; __device__ __forceinline__ void head_ss(const f32x4 (&v)[2][2][4][2], float (&tot)[2][4][2], LAS float* X, int wr, int wc, int fr, int fq) {
;     ...
;                 const f32x4 a = v[ai][bj][m][0], b = v[ai][bj][m][1];
;                 float s = (a[0] * a[0] + a[1] * a[1]) + (a[2] * a[2] + a[3] * a[3]) + (b[0] * b[0] + b[1] * b[1]) + (b[2] * b[2] + b[3] * b[3]);
;                 s += __shfl_xor(s, 16); s += __shfl_xor(s, 32);
;                 if (fq == 0) X[((ai * 128 + wr * 64 + m * 16 + fr) * 2 + bj) * 4 + wc] = s;
;             }
.LBB0_1069:
	s_or_b64 exec, exec, s[42:43]
	v_mul_f32_e32 v46, v49, v49
	v_mul_f32_e32 v45, v45, v45
	v_fmac_f32_e32 v46, v48, v48
	v_fmac_f32_e32 v45, v44, v44
	v_mul_f32_e32 v41, v41, v41
	v_add_f32_e32 v44, v46, v45
	v_fmac_f32_e32 v41, v40, v40
	v_add_f32_e32 v40, v41, v44
	v_mul_f32_e32 v41, v43, v43
	v_fmac_f32_e32 v41, v42, v42
	v_add_f32_e32 v40, v41, v40
	v_mov_b32_e32 v41, v40
	s_nop 1
	v_permlane16_swap_b32_e32 v41, v40
	v_add_f32_e32 v40, v40, v41
	v_mov_b32_e32 v41, v40
	s_nop 1
	v_permlane32_swap_b32_e32 v41, v40
	s_and_saveexec_b64 s[42:43], s[0:1]
	s_cbranch_execz .LBB0_1071
	v_add_f32_e32 v40, v40, v41
	ds_write_b32 v19, v40 offset:4608
.LBB0_1071:
	s_or_b64 exec, exec, s[42:43]
	v_mul_f32_e32 v37, v37, v37
	v_fmac_f32_e32 v37, v36, v36
	v_mul_f32_e32 v36, v39, v39
	v_fmac_f32_e32 v36, v38, v38
	v_add_f32_e32 v36, v37, v36
	v_mul_f32_e32 v37, v51, v51
	v_fmac_f32_e32 v37, v50, v50
	v_mul_f32_e32 v31, v31, v31
	v_add_f32_e32 v36, v37, v36
	v_fmac_f32_e32 v31, v30, v30
	v_add_f32_e32 v30, v31, v36
	v_mov_b32_e32 v31, v30
	s_nop 1
	v_permlane16_swap_b32_e32 v31, v30
	v_add_f32_e32 v30, v30, v31
	v_mov_b32_e32 v31, v30
	s_nop 1
	v_permlane32_swap_b32_e32 v31, v30
	s_and_saveexec_b64 s[42:43], s[0:1]
	s_cbranch_execz .LBB0_1073
	v_add_f32_e32 v30, v30, v31
	ds_write_b32 v19, v30 offset:4624
.LBB0_1073:
	s_or_b64 exec, exec, s[42:43]
	v_mul_f32_e32 v30, v33, v33
	v_mul_f32_e32 v29, v29, v29
	v_fmac_f32_e32 v30, v32, v32
	v_fmac_f32_e32 v29, v28, v28
	v_mul_f32_e32 v25, v25, v25
	v_add_f32_e32 v28, v30, v29
	v_fmac_f32_e32 v25, v24, v24
	v_add_f32_e32 v24, v25, v28
	v_mul_f32_e32 v25, v27, v27
	v_fmac_f32_e32 v25, v26, v26
	v_add_f32_e32 v24, v25, v24
	v_mov_b32_e32 v25, v24
	s_nop 1
	v_permlane16_swap_b32_e32 v25, v24
	v_add_f32_e32 v24, v24, v25
	v_mov_b32_e32 v25, v24
	s_nop 1
	v_permlane32_swap_b32_e32 v25, v24
	s_and_saveexec_b64 s[42:43], s[0:1]
	s_cbranch_execz .LBB0_1075
	v_add_f32_e32 v24, v24, v25
	ds_write_b32 v19, v24 offset:5120
.LBB0_1075:
	s_or_b64 exec, exec, s[42:43]
	v_mul_f32_e32 v21, v21, v21
	v_fmac_f32_e32 v21, v20, v20
	v_mul_f32_e32 v20, v23, v23
	v_fmac_f32_e32 v20, v22, v22
	v_add_f32_e32 v20, v21, v20
	v_mul_f32_e32 v21, v35, v35
	v_fmac_f32_e32 v21, v34, v34
	v_mul_f32_e32 v15, v15, v15
	v_add_f32_e32 v20, v21, v20
	v_fmac_f32_e32 v15, v14, v14
	v_add_f32_e32 v14, v15, v20
	v_mov_b32_e32 v15, v14
	s_nop 1
	v_permlane16_swap_b32_e32 v15, v14
	v_add_f32_e32 v14, v14, v15
	v_mov_b32_e32 v15, v14
	s_nop 1
	v_permlane32_swap_b32_e32 v15, v14
	s_and_saveexec_b64 s[42:43], s[0:1]
	s_cbranch_execz .LBB0_1077
	v_add_f32_e32 v14, v14, v15
	ds_write_b32 v19, v14 offset:5136
.LBB0_1077:
	s_or_b64 exec, exec, s[42:43]
	v_mul_f32_e32 v14, v17, v17
	v_mul_f32_e32 v13, v13, v13
	v_fmac_f32_e32 v14, v16, v16
	v_fmac_f32_e32 v13, v12, v12
	v_mul_f32_e32 v9, v9, v9
	v_add_f32_e32 v12, v14, v13
	v_fmac_f32_e32 v9, v8, v8
	v_add_f32_e32 v8, v9, v12
	v_mul_f32_e32 v9, v11, v11
	v_fmac_f32_e32 v9, v10, v10
	v_add_f32_e32 v8, v9, v8
	v_mov_b32_e32 v9, v8
	s_nop 1
	v_permlane16_swap_b32_e32 v9, v8
	v_add_f32_e32 v8, v8, v9
	v_mov_b32_e32 v9, v8
	s_nop 1
	v_permlane32_swap_b32_e32 v9, v8
	s_and_saveexec_b64 s[42:43], s[0:1]
	s_cbranch_execz .LBB0_1079
	v_add_f32_e32 v8, v8, v9
	ds_write_b32 v19, v8 offset:5632
.LBB0_1079:
	s_or_b64 exec, exec, s[42:43]
	v_mul_f32_e32 v5, v5, v5
	v_fmac_f32_e32 v5, v4, v4
	v_mul_f32_e32 v4, v7, v7
	v_fmac_f32_e32 v4, v6, v6
	v_mul_f32_e32 v1, v1, v1
	v_add_f32_e32 v4, v5, v4
	v_fmac_f32_e32 v1, v0, v0
	v_add_f32_e32 v0, v1, v4
	v_mul_f32_e32 v1, v3, v3
	v_fmac_f32_e32 v1, v2, v2
	v_add_f32_e32 v0, v1, v0
	v_mov_b32_e32 v1, v0
	s_nop 1
	v_permlane16_swap_b32_e32 v1, v0
	v_add_f32_e32 v0, v0, v1
	v_mov_b32_e32 v1, v0
	s_nop 1
	v_permlane32_swap_b32_e32 v1, v0
	s_and_saveexec_b64 s[42:43], s[0:1]
	s_cbranch_execz .LBB0_1081
	v_add_f32_e32 v0, v0, v1
	ds_write_b32 v19, v0 offset:5648
